# GEMM K-loops software-pipelined with double-buffered fragments (spare VGPRs), DMA A-group right after barrier and B-group after 2nd read issue; RWKV scan triangular solve LDS reads prefetched through
# speedup vs baseline: 1.0099x; 1.0099x over previous
; DI f32x4 mfma16(bf16x8 a, bf16x8 b, f32x4 c) { return __builtin_amdgcn_mfma_f32_16x16x32_bf16(a, b, c, 0, 0, 0); }
;     ...
; #pragma unroll 1
;   for (int kt = 0; kt < nk; ++kt) {
;     const bool issue = kt + 1 < nk;
;     const int ibuf = buf ^ 1;
; #pragma unroll
;     for (int s2 = 0; s2 < 2; ++s2) {
;       bf16x8 bf[4], af[MF];
;       {
;         const unsigned la = lds_base + buf * 65536 + ((wm * MF) << 11) + (s2 ? lofs1 : lofs0);
;         const unsigned lb = lds_base + buf * 65536 + 32768 + ((wn * 4) << 11) + (s2 ? lofs1 : lofs0);
;         if constexpr (MF == 8) {
;           asm volatile(
;               "ds_read_b128 %0, %13\n\tds_read_b128 %1, %13 offset:2048\n\tds_read_b128 %2, %13 offset:4096\n\tds_read_b128 %3, %13 offset:6144\n\t"
;               "ds_read_b128 %4, %12\n\tds_read_b128 %5, %12 offset:2048\n\tds_read_b128 %6, %12 offset:4096\n\tds_read_b128 %7, %12 offset:6144\n\t"
;               "ds_read_b128 %8, %12 offset:8192\n\tds_read_b128 %9, %12 offset:10240\n\tds_read_b128 %10, %12 offset:12288\n\tds_read_b128 %11, %12 offset:14336\n\t"
;               "s_waitcnt lgkmcnt(0)"
;               : "=&v"(bf[0]), "=&v"(bf[1]), "=&v"(bf[2]), "=&v"(bf[3]), "=&v"(af[0]), "=&v"(af[1]), "=&v"(af[2]), "=&v"(af[3]),
;                 "=&v"(af[4]), "=&v"(af[5]), "=&v"(af[6]), "=&v"(af[7])
;               : "v"(la), "v"(lb)
;               : "memory");
;         } else {
;           asm volatile(
;               "ds_read_b128 %0, %9\n\tds_read_b128 %1, %9 offset:2048\n\tds_read_b128 %2, %9 offset:4096\n\tds_read_b128 %3, %9 offset:6144\n\t"
;               "ds_read_b128 %4, %8\n\tds_read_b128 %5, %8 offset:2048\n\tds_read_b128 %6, %8 offset:4096\n\tds_read_b128 %7, %8 offset:6144\n\t"
;               "s_waitcnt lgkmcnt(0)"
;               : "=&v"(bf[0]), "=&v"(bf[1]), "=&v"(bf[2]), "=&v"(bf[3]), "=&v"(af[0]), "=&v"(af[1]), "=&v"(af[2]), "=&v"(af[3])
;               : "v"(la), "v"(lb)
;               : "memory");
;         }
;       }
;       __builtin_amdgcn_sched_barrier(0);
;       __builtin_amdgcn_s_setprio(1);
; #pragma unroll
;       for (int m = 0; m < MF; ++m) {
; #pragma unroll
;         for (int n = 0; n < 4; ++n) acc[m][n] = mfma16(bf[n], af[m], acc[m][n]);
;         if constexpr (MF == 8) {
;           if (m & 1) {
;             __builtin_amdgcn_sched_barrier(0);
;             if (issue) {
.LBB0_354:
	s_mov_b32 s2, s6
	s_cmp_lg_u32 s5, 1
	s_cselect_b64 s[0:1], -1, 0
	s_lshl_b32 s2, s2, 16
	v_add3_u32 v234, s2, v178, v180
	v_add3_u32 v235, s2, v179, v180
	ds_read_b128 v[128:131], v235
	ds_read_b128 v[132:135], v235 offset:2048
	ds_read_b128 v[136:139], v235 offset:4096
	ds_read_b128 v[140:143], v235 offset:6144
	ds_read_b128 v[144:147], v234
	ds_read_b128 v[148:151], v234 offset:2048
	ds_read_b128 v[152:155], v234 offset:4096
	ds_read_b128 v[156:159], v234 offset:6144
	ds_read_b128 v[160:163], v234 offset:8192
	ds_read_b128 v[164:167], v234 offset:10240
	ds_read_b128 v[194:197], v234 offset:12288
	ds_read_b128 v[198:201], v234 offset:14336
	v_add3_u32 v234, s2, v178, v181
	v_add3_u32 v235, s2, v179, v181
	s_xor_b32 s6, s6, 1
	s_lshl_b32 s3, s6, 16
	v_readfirstlane_b32 s98, v177
	s_add_u32 s98, s98, s3
	s_cmp_eq_u64 s[0:1], 0
	s_cbranch_scc1 .Lgp0_na
	s_mov_b32 m0, s98
	s_nop 0
	global_load_lds_dwordx4 v[172:173], off
	s_add_u32 m0, s98, 0x400
	v_lshl_add_u64 v[254:255], v[172:173], 0, s[24:25]
	global_load_lds_dwordx4 v[254:255], off
	s_add_u32 m0, s98, 0x800
	v_lshl_add_u64 v[254:255], v[172:173], 0, s[26:27]
	global_load_lds_dwordx4 v[254:255], off
	s_add_u32 m0, s98, 0xc00
	v_lshl_add_u64 v[254:255], v[172:173], 0, s[28:29]
	global_load_lds_dwordx4 v[254:255], off
.Lgp0_na:
	s_setprio 1
	v_mfma_f32_16x16x32_bf16 v[124:127], v[202:205], v[218:221], v[124:127]
	v_mfma_f32_16x16x32_bf16 v[120:123], v[206:209], v[218:221], v[120:123]
	v_mfma_f32_16x16x32_bf16 v[116:119], v[210:213], v[218:221], v[116:119]
	v_mfma_f32_16x16x32_bf16 v[112:115], v[214:217], v[218:221], v[112:115]
	v_mfma_f32_16x16x32_bf16 v[108:111], v[202:205], v[222:225], v[108:111]
	v_mfma_f32_16x16x32_bf16 v[104:107], v[206:209], v[222:225], v[104:107]
	v_mfma_f32_16x16x32_bf16 v[100:103], v[210:213], v[222:225], v[100:103]
	v_mfma_f32_16x16x32_bf16 v[96:99], v[214:217], v[222:225], v[96:99]
	v_mfma_f32_16x16x32_bf16 v[92:95], v[202:205], v[226:229], v[92:95]
	v_mfma_f32_16x16x32_bf16 v[88:91], v[206:209], v[226:229], v[88:91]
	v_mfma_f32_16x16x32_bf16 v[84:87], v[210:213], v[226:229], v[84:87]
	v_mfma_f32_16x16x32_bf16 v[80:83], v[214:217], v[226:229], v[80:83]
	v_mfma_f32_16x16x32_bf16 v[76:79], v[202:205], v[230:233], v[76:79]
	v_mfma_f32_16x16x32_bf16 v[72:75], v[206:209], v[230:233], v[72:75]
	v_mfma_f32_16x16x32_bf16 v[68:71], v[210:213], v[230:233], v[68:71]
	v_mfma_f32_16x16x32_bf16 v[64:67], v[214:217], v[230:233], v[64:67]
	v_mfma_f32_16x16x32_bf16 v[60:63], v[202:205], v[238:241], v[60:63]
	v_mfma_f32_16x16x32_bf16 v[56:59], v[206:209], v[238:241], v[56:59]
	v_mfma_f32_16x16x32_bf16 v[52:55], v[210:213], v[238:241], v[52:55]
	v_mfma_f32_16x16x32_bf16 v[48:51], v[214:217], v[238:241], v[48:51]
	v_mfma_f32_16x16x32_bf16 v[44:47], v[202:205], v[242:245], v[44:47]
	v_mfma_f32_16x16x32_bf16 v[40:43], v[206:209], v[242:245], v[40:43]
	v_mfma_f32_16x16x32_bf16 v[32:35], v[210:213], v[242:245], v[32:35]
	v_mfma_f32_16x16x32_bf16 v[20:23], v[214:217], v[242:245], v[20:23]
	v_mfma_f32_16x16x32_bf16 v[36:39], v[202:205], v[246:249], v[36:39]
	v_mfma_f32_16x16x32_bf16 v[28:31], v[206:209], v[246:249], v[28:31]
	v_mfma_f32_16x16x32_bf16 v[24:27], v[210:213], v[246:249], v[24:27]
	v_mfma_f32_16x16x32_bf16 v[16:19], v[214:217], v[246:249], v[16:19]
	v_mfma_f32_16x16x32_bf16 v[12:15], v[202:205], v[250:253], v[12:15]
	v_mfma_f32_16x16x32_bf16 v[8:11], v[206:209], v[250:253], v[8:11]
	v_mfma_f32_16x16x32_bf16 v[4:7], v[210:213], v[250:253], v[4:7]
	v_mfma_f32_16x16x32_bf16 v[0:3], v[214:217], v[250:253], v[0:3]
	s_setprio 0
.Lgp0_mid:
	s_waitcnt lgkmcnt(0)
	ds_read_b128 v[202:205], v235
	ds_read_b128 v[206:209], v235 offset:2048
	ds_read_b128 v[210:213], v235 offset:4096
	ds_read_b128 v[214:217], v235 offset:6144
	ds_read_b128 v[218:221], v234
	ds_read_b128 v[222:225], v234 offset:2048
	ds_read_b128 v[226:229], v234 offset:4096
	ds_read_b128 v[230:233], v234 offset:6144
	ds_read_b128 v[238:241], v234 offset:8192
	ds_read_b128 v[242:245], v234 offset:10240
	ds_read_b128 v[246:249], v234 offset:12288
	ds_read_b128 v[250:253], v234 offset:14336
	s_cmp_eq_u64 s[0:1], 0
	s_cbranch_scc1 .Lgp0_nb
	s_add_u32 m0, s98, 0x8000
	s_nop 0
	global_load_lds_dwordx4 v[174:175], off
	s_add_u32 m0, s98, 0x8400
	v_lshl_add_u64 v[254:255], v[174:175], 0, s[24:25]
	global_load_lds_dwordx4 v[254:255], off
	s_add_u32 m0, s98, 0x8800
	v_lshl_add_u64 v[254:255], v[174:175], 0, s[26:27]
	global_load_lds_dwordx4 v[254:255], off
	s_add_u32 m0, s98, 0x8c00
	v_lshl_add_u64 v[254:255], v[174:175], 0, s[28:29]
	global_load_lds_dwordx4 v[254:255], off
.Lgp0_nb:
	s_setprio 1
	v_mfma_f32_16x16x32_bf16 v[124:127], v[128:131], v[144:147], v[124:127]
	v_mfma_f32_16x16x32_bf16 v[120:123], v[132:135], v[144:147], v[120:123]
	v_mfma_f32_16x16x32_bf16 v[116:119], v[136:139], v[144:147], v[116:119]
	v_mfma_f32_16x16x32_bf16 v[112:115], v[140:143], v[144:147], v[112:115]
	v_mfma_f32_16x16x32_bf16 v[108:111], v[128:131], v[148:151], v[108:111]
	v_mfma_f32_16x16x32_bf16 v[104:107], v[132:135], v[148:151], v[104:107]
	v_mfma_f32_16x16x32_bf16 v[100:103], v[136:139], v[148:151], v[100:103]
	v_mfma_f32_16x16x32_bf16 v[96:99], v[140:143], v[148:151], v[96:99]
	v_mfma_f32_16x16x32_bf16 v[92:95], v[128:131], v[152:155], v[92:95]
	v_mfma_f32_16x16x32_bf16 v[88:91], v[132:135], v[152:155], v[88:91]
	v_mfma_f32_16x16x32_bf16 v[84:87], v[136:139], v[152:155], v[84:87]
	v_mfma_f32_16x16x32_bf16 v[80:83], v[140:143], v[152:155], v[80:83]
	v_mfma_f32_16x16x32_bf16 v[76:79], v[128:131], v[156:159], v[76:79]
	v_mfma_f32_16x16x32_bf16 v[72:75], v[132:135], v[156:159], v[72:75]
	v_mfma_f32_16x16x32_bf16 v[68:71], v[136:139], v[156:159], v[68:71]
	v_mfma_f32_16x16x32_bf16 v[64:67], v[140:143], v[156:159], v[64:67]
	v_mfma_f32_16x16x32_bf16 v[60:63], v[128:131], v[160:163], v[60:63]
	v_mfma_f32_16x16x32_bf16 v[56:59], v[132:135], v[160:163], v[56:59]
	v_mfma_f32_16x16x32_bf16 v[52:55], v[136:139], v[160:163], v[52:55]
	v_mfma_f32_16x16x32_bf16 v[48:51], v[140:143], v[160:163], v[48:51]
	v_mfma_f32_16x16x32_bf16 v[44:47], v[128:131], v[164:167], v[44:47]
	v_mfma_f32_16x16x32_bf16 v[40:43], v[132:135], v[164:167], v[40:43]
	v_mfma_f32_16x16x32_bf16 v[32:35], v[136:139], v[164:167], v[32:35]
	v_mfma_f32_16x16x32_bf16 v[20:23], v[140:143], v[164:167], v[20:23]
	v_mfma_f32_16x16x32_bf16 v[36:39], v[128:131], v[194:197], v[36:39]
	v_mfma_f32_16x16x32_bf16 v[28:31], v[132:135], v[194:197], v[28:31]
	v_mfma_f32_16x16x32_bf16 v[24:27], v[136:139], v[194:197], v[24:27]
	v_mfma_f32_16x16x32_bf16 v[16:19], v[140:143], v[194:197], v[16:19]
	v_mfma_f32_16x16x32_bf16 v[12:15], v[128:131], v[198:201], v[12:15]
	v_mfma_f32_16x16x32_bf16 v[8:11], v[132:135], v[198:201], v[8:11]
	v_mfma_f32_16x16x32_bf16 v[4:7], v[136:139], v[198:201], v[4:7]
	v_mfma_f32_16x16x32_bf16 v[0:3], v[140:143], v[198:201], v[0:3]
	s_setprio 0
	s_waitcnt lgkmcnt(0)
	s_and_b64 s[0:1], s[0:1], 0x80
	s_branch .LBB0_353

; DI f32x4 mfma16(bf16x8 a, bf16x8 b, f32x4 c) { return __builtin_amdgcn_mfma_f32_16x16x32_bf16(a, b, c, 0, 0, 0); }
;     ...
;       for (int m = 0; m < MF; ++m) {
; #pragma unroll
;         for (int n = 0; n < 4; ++n) acc[m][n] = mfma16(bf[n], af[m], acc[m][n]);
.Lgp0_exit:
	s_setprio 1
	v_mfma_f32_16x16x32_bf16 v[124:127], v[202:205], v[218:221], v[124:127]
	v_mfma_f32_16x16x32_bf16 v[120:123], v[206:209], v[218:221], v[120:123]
	v_mfma_f32_16x16x32_bf16 v[116:119], v[210:213], v[218:221], v[116:119]
	v_mfma_f32_16x16x32_bf16 v[112:115], v[214:217], v[218:221], v[112:115]
	v_mfma_f32_16x16x32_bf16 v[108:111], v[202:205], v[222:225], v[108:111]
	v_mfma_f32_16x16x32_bf16 v[104:107], v[206:209], v[222:225], v[104:107]
	v_mfma_f32_16x16x32_bf16 v[100:103], v[210:213], v[222:225], v[100:103]
	v_mfma_f32_16x16x32_bf16 v[96:99], v[214:217], v[222:225], v[96:99]
	v_mfma_f32_16x16x32_bf16 v[92:95], v[202:205], v[226:229], v[92:95]
	v_mfma_f32_16x16x32_bf16 v[88:91], v[206:209], v[226:229], v[88:91]
	v_mfma_f32_16x16x32_bf16 v[84:87], v[210:213], v[226:229], v[84:87]
	v_mfma_f32_16x16x32_bf16 v[80:83], v[214:217], v[226:229], v[80:83]
	v_mfma_f32_16x16x32_bf16 v[76:79], v[202:205], v[230:233], v[76:79]
	v_mfma_f32_16x16x32_bf16 v[72:75], v[206:209], v[230:233], v[72:75]
	v_mfma_f32_16x16x32_bf16 v[68:71], v[210:213], v[230:233], v[68:71]
	v_mfma_f32_16x16x32_bf16 v[64:67], v[214:217], v[230:233], v[64:67]
	v_mfma_f32_16x16x32_bf16 v[60:63], v[202:205], v[238:241], v[60:63]
	v_mfma_f32_16x16x32_bf16 v[56:59], v[206:209], v[238:241], v[56:59]
	v_mfma_f32_16x16x32_bf16 v[52:55], v[210:213], v[238:241], v[52:55]
	v_mfma_f32_16x16x32_bf16 v[48:51], v[214:217], v[238:241], v[48:51]
	v_mfma_f32_16x16x32_bf16 v[44:47], v[202:205], v[242:245], v[44:47]
	v_mfma_f32_16x16x32_bf16 v[40:43], v[206:209], v[242:245], v[40:43]
	v_mfma_f32_16x16x32_bf16 v[32:35], v[210:213], v[242:245], v[32:35]
	v_mfma_f32_16x16x32_bf16 v[20:23], v[214:217], v[242:245], v[20:23]
	v_mfma_f32_16x16x32_bf16 v[36:39], v[202:205], v[246:249], v[36:39]
	v_mfma_f32_16x16x32_bf16 v[28:31], v[206:209], v[246:249], v[28:31]
	v_mfma_f32_16x16x32_bf16 v[24:27], v[210:213], v[246:249], v[24:27]
	v_mfma_f32_16x16x32_bf16 v[16:19], v[214:217], v[246:249], v[16:19]
	v_mfma_f32_16x16x32_bf16 v[12:15], v[202:205], v[250:253], v[12:15]
	v_mfma_f32_16x16x32_bf16 v[8:11], v[206:209], v[250:253], v[8:11]
	v_mfma_f32_16x16x32_bf16 v[4:7], v[210:213], v[250:253], v[4:7]
	v_mfma_f32_16x16x32_bf16 v[0:3], v[214:217], v[250:253], v[0:3]
	s_setprio 0
	s_nop 7
	s_nop 3
	s_branch .LBB0_370

; DI f32x4 mfma16(bf16x8 a, bf16x8 b, f32x4 c) { return __builtin_amdgcn_mfma_f32_16x16x32_bf16(a, b, c, 0, 0, 0); }
;     ...
; #pragma unroll 1
;   for (int kt = 0; kt < nk; ++kt) {
;     const bool issue = kt + 1 < nk;
;     const int ibuf = buf ^ 1;
; #pragma unroll
;     for (int s2 = 0; s2 < 2; ++s2) {
;       bf16x8 bf[4], af[MF];
;       {
;         const unsigned la = lds_base + buf * 65536 + ((wm * MF) << 11) + (s2 ? lofs1 : lofs0);
;         const unsigned lb = lds_base + buf * 65536 + 32768 + ((wn * 4) << 11) + (s2 ? lofs1 : lofs0);
;         if constexpr (MF == 8) {
;           asm volatile(
;               "ds_read_b128 %0, %13\n\tds_read_b128 %1, %13 offset:2048\n\tds_read_b128 %2, %13 offset:4096\n\tds_read_b128 %3, %13 offset:6144\n\t"
;               "ds_read_b128 %4, %12\n\tds_read_b128 %5, %12 offset:2048\n\tds_read_b128 %6, %12 offset:4096\n\tds_read_b128 %7, %12 offset:6144\n\t"
;               "ds_read_b128 %8, %12 offset:8192\n\tds_read_b128 %9, %12 offset:10240\n\tds_read_b128 %10, %12 offset:12288\n\tds_read_b128 %11, %12 offset:14336\n\t"
;               "s_waitcnt lgkmcnt(0)"
;               : "=&v"(bf[0]), "=&v"(bf[1]), "=&v"(bf[2]), "=&v"(bf[3]), "=&v"(af[0]), "=&v"(af[1]), "=&v"(af[2]), "=&v"(af[3]),
;                 "=&v"(af[4]), "=&v"(af[5]), "=&v"(af[6]), "=&v"(af[7])
;               : "v"(la), "v"(lb)
;               : "memory");
;         } else {
;           asm volatile(
;               "ds_read_b128 %0, %9\n\tds_read_b128 %1, %9 offset:2048\n\tds_read_b128 %2, %9 offset:4096\n\tds_read_b128 %3, %9 offset:6144\n\t"
;               "ds_read_b128 %4, %8\n\tds_read_b128 %5, %8 offset:2048\n\tds_read_b128 %6, %8 offset:4096\n\tds_read_b128 %7, %8 offset:6144\n\t"
;               "s_waitcnt lgkmcnt(0)"
;               : "=&v"(bf[0]), "=&v"(bf[1]), "=&v"(bf[2]), "=&v"(bf[3]), "=&v"(af[0]), "=&v"(af[1]), "=&v"(af[2]), "=&v"(af[3])
;               : "v"(la), "v"(lb)
;               : "memory");
;         }
;       }
;       __builtin_amdgcn_sched_barrier(0);
;       __builtin_amdgcn_s_setprio(1);
; #pragma unroll
;       for (int m = 0; m < MF; ++m) {
; #pragma unroll
;         for (int n = 0; n < 4; ++n) acc[m][n] = mfma16(bf[n], af[m], acc[m][n]);
;         if constexpr (MF == 8) {
;           if (m & 1) {
;             __builtin_amdgcn_sched_barrier(0);
;             if (issue) {
.LBB0_535:
	s_mov_b32 s4, s30
	s_cmp_lt_u32 s29, 43
	s_cselect_b64 s[20:21], -1, 0
	s_lshl_b32 s4, s4, 16
	v_add3_u32 v234, s4, v168, v181
	v_add3_u32 v235, s4, v180, v181
	ds_read_b128 v[128:131], v235
	ds_read_b128 v[132:135], v235 offset:2048
	ds_read_b128 v[136:139], v235 offset:4096
	ds_read_b128 v[140:143], v235 offset:6144
	ds_read_b128 v[144:147], v234
	ds_read_b128 v[148:151], v234 offset:2048
	ds_read_b128 v[152:155], v234 offset:4096
	ds_read_b128 v[156:159], v234 offset:6144
	ds_read_b128 v[160:163], v234 offset:8192
	ds_read_b128 v[164:167], v234 offset:10240
	ds_read_b128 v[194:197], v234 offset:12288
	ds_read_b128 v[198:201], v234 offset:14336
	v_add3_u32 v234, s4, v168, v182
	v_add3_u32 v235, s4, v180, v182
	s_xor_b32 s30, s30, 1
	s_lshl_b32 s5, s30, 16
	v_readfirstlane_b32 s98, v179
	s_add_u32 s98, s98, s5
	s_cmp_eq_u64 s[20:21], 0
	s_cbranch_scc1 .Lgp2_na
	s_mov_b32 m0, s98
	s_nop 0
	global_load_lds_dwordx4 v[174:175], off
	s_add_u32 m0, s98, 0x400
	v_lshl_add_u64 v[254:255], v[174:175], 0, s[14:15]
	global_load_lds_dwordx4 v[254:255], off
	s_add_u32 m0, s98, 0x800
	v_lshl_add_u64 v[254:255], v[174:175], 0, s[16:17]
	global_load_lds_dwordx4 v[254:255], off
	s_add_u32 m0, s98, 0xc00
	v_lshl_add_u64 v[254:255], v[174:175], 0, s[18:19]
	global_load_lds_dwordx4 v[254:255], off
.Lgp2_na:
	s_setprio 1
	v_mfma_f32_16x16x32_bf16 v[124:127], v[202:205], v[218:221], v[124:127]
	v_mfma_f32_16x16x32_bf16 v[120:123], v[206:209], v[218:221], v[120:123]
	v_mfma_f32_16x16x32_bf16 v[116:119], v[210:213], v[218:221], v[116:119]
	v_mfma_f32_16x16x32_bf16 v[112:115], v[214:217], v[218:221], v[112:115]
	v_mfma_f32_16x16x32_bf16 v[108:111], v[202:205], v[222:225], v[108:111]
	v_mfma_f32_16x16x32_bf16 v[104:107], v[206:209], v[222:225], v[104:107]
	v_mfma_f32_16x16x32_bf16 v[100:103], v[210:213], v[222:225], v[100:103]
	v_mfma_f32_16x16x32_bf16 v[96:99], v[214:217], v[222:225], v[96:99]
	v_mfma_f32_16x16x32_bf16 v[92:95], v[202:205], v[226:229], v[92:95]
	v_mfma_f32_16x16x32_bf16 v[88:91], v[206:209], v[226:229], v[88:91]
	v_mfma_f32_16x16x32_bf16 v[84:87], v[210:213], v[226:229], v[84:87]
	v_mfma_f32_16x16x32_bf16 v[80:83], v[214:217], v[226:229], v[80:83]
	v_mfma_f32_16x16x32_bf16 v[76:79], v[202:205], v[230:233], v[76:79]
	v_mfma_f32_16x16x32_bf16 v[72:75], v[206:209], v[230:233], v[72:75]
	v_mfma_f32_16x16x32_bf16 v[68:71], v[210:213], v[230:233], v[68:71]
	v_mfma_f32_16x16x32_bf16 v[64:67], v[214:217], v[230:233], v[64:67]
	v_mfma_f32_16x16x32_bf16 v[60:63], v[202:205], v[238:241], v[60:63]
	v_mfma_f32_16x16x32_bf16 v[56:59], v[206:209], v[238:241], v[56:59]
	v_mfma_f32_16x16x32_bf16 v[52:55], v[210:213], v[238:241], v[52:55]
	v_mfma_f32_16x16x32_bf16 v[48:51], v[214:217], v[238:241], v[48:51]
	v_mfma_f32_16x16x32_bf16 v[44:47], v[202:205], v[242:245], v[44:47]
	v_mfma_f32_16x16x32_bf16 v[40:43], v[206:209], v[242:245], v[40:43]
	v_mfma_f32_16x16x32_bf16 v[36:39], v[210:213], v[242:245], v[36:39]
	v_mfma_f32_16x16x32_bf16 v[32:35], v[214:217], v[242:245], v[32:35]
	v_mfma_f32_16x16x32_bf16 v[28:31], v[202:205], v[246:249], v[28:31]
	v_mfma_f32_16x16x32_bf16 v[24:27], v[206:209], v[246:249], v[24:27]
	v_mfma_f32_16x16x32_bf16 v[20:23], v[210:213], v[246:249], v[20:23]
	v_mfma_f32_16x16x32_bf16 v[16:19], v[214:217], v[246:249], v[16:19]
	v_mfma_f32_16x16x32_bf16 v[12:15], v[202:205], v[250:253], v[12:15]
	v_mfma_f32_16x16x32_bf16 v[8:11], v[206:209], v[250:253], v[8:11]
	v_mfma_f32_16x16x32_bf16 v[4:7], v[210:213], v[250:253], v[4:7]
	v_mfma_f32_16x16x32_bf16 v[0:3], v[214:217], v[250:253], v[0:3]
	s_setprio 0
.Lgp2_mid:
	s_waitcnt lgkmcnt(0)
	ds_read_b128 v[202:205], v235
	ds_read_b128 v[206:209], v235 offset:2048
	ds_read_b128 v[210:213], v235 offset:4096
	ds_read_b128 v[214:217], v235 offset:6144
	ds_read_b128 v[218:221], v234
	ds_read_b128 v[222:225], v234 offset:2048
	ds_read_b128 v[226:229], v234 offset:4096
	ds_read_b128 v[230:233], v234 offset:6144
	ds_read_b128 v[238:241], v234 offset:8192
	ds_read_b128 v[242:245], v234 offset:10240
	ds_read_b128 v[246:249], v234 offset:12288
	ds_read_b128 v[250:253], v234 offset:14336
	s_cmp_eq_u64 s[20:21], 0
	s_cbranch_scc1 .Lgp2_nb
	s_add_u32 m0, s98, 0x8000
	s_nop 0
	global_load_lds_dwordx4 v[176:177], off
	s_add_u32 m0, s98, 0x8400
	v_lshl_add_u64 v[254:255], v[176:177], 0, s[14:15]
	global_load_lds_dwordx4 v[254:255], off
	s_add_u32 m0, s98, 0x8800
	v_lshl_add_u64 v[254:255], v[176:177], 0, s[16:17]
	global_load_lds_dwordx4 v[254:255], off
	s_add_u32 m0, s98, 0x8c00
	v_lshl_add_u64 v[254:255], v[176:177], 0, s[18:19]
	global_load_lds_dwordx4 v[254:255], off
.Lgp2_nb:
	s_setprio 1
	v_mfma_f32_16x16x32_bf16 v[124:127], v[128:131], v[144:147], v[124:127]
	v_mfma_f32_16x16x32_bf16 v[120:123], v[132:135], v[144:147], v[120:123]
	v_mfma_f32_16x16x32_bf16 v[116:119], v[136:139], v[144:147], v[116:119]
	v_mfma_f32_16x16x32_bf16 v[112:115], v[140:143], v[144:147], v[112:115]
	v_mfma_f32_16x16x32_bf16 v[108:111], v[128:131], v[148:151], v[108:111]
	v_mfma_f32_16x16x32_bf16 v[104:107], v[132:135], v[148:151], v[104:107]
	v_mfma_f32_16x16x32_bf16 v[100:103], v[136:139], v[148:151], v[100:103]
	v_mfma_f32_16x16x32_bf16 v[96:99], v[140:143], v[148:151], v[96:99]
	v_mfma_f32_16x16x32_bf16 v[92:95], v[128:131], v[152:155], v[92:95]
	v_mfma_f32_16x16x32_bf16 v[88:91], v[132:135], v[152:155], v[88:91]
	v_mfma_f32_16x16x32_bf16 v[84:87], v[136:139], v[152:155], v[84:87]
	v_mfma_f32_16x16x32_bf16 v[80:83], v[140:143], v[152:155], v[80:83]
	v_mfma_f32_16x16x32_bf16 v[76:79], v[128:131], v[156:159], v[76:79]
	v_mfma_f32_16x16x32_bf16 v[72:75], v[132:135], v[156:159], v[72:75]
	v_mfma_f32_16x16x32_bf16 v[68:71], v[136:139], v[156:159], v[68:71]
	v_mfma_f32_16x16x32_bf16 v[64:67], v[140:143], v[156:159], v[64:67]
	v_mfma_f32_16x16x32_bf16 v[60:63], v[128:131], v[160:163], v[60:63]
	v_mfma_f32_16x16x32_bf16 v[56:59], v[132:135], v[160:163], v[56:59]
	v_mfma_f32_16x16x32_bf16 v[52:55], v[136:139], v[160:163], v[52:55]
	v_mfma_f32_16x16x32_bf16 v[48:51], v[140:143], v[160:163], v[48:51]
	v_mfma_f32_16x16x32_bf16 v[44:47], v[128:131], v[164:167], v[44:47]
	v_mfma_f32_16x16x32_bf16 v[40:43], v[132:135], v[164:167], v[40:43]
	v_mfma_f32_16x16x32_bf16 v[36:39], v[136:139], v[164:167], v[36:39]
	v_mfma_f32_16x16x32_bf16 v[32:35], v[140:143], v[164:167], v[32:35]
	v_mfma_f32_16x16x32_bf16 v[28:31], v[128:131], v[194:197], v[28:31]
	v_mfma_f32_16x16x32_bf16 v[24:27], v[132:135], v[194:197], v[24:27]
	v_mfma_f32_16x16x32_bf16 v[20:23], v[136:139], v[194:197], v[20:23]
	v_mfma_f32_16x16x32_bf16 v[16:19], v[140:143], v[194:197], v[16:19]
	v_mfma_f32_16x16x32_bf16 v[12:15], v[128:131], v[198:201], v[12:15]
	v_mfma_f32_16x16x32_bf16 v[8:11], v[132:135], v[198:201], v[8:11]
	v_mfma_f32_16x16x32_bf16 v[4:7], v[136:139], v[198:201], v[4:7]
	v_mfma_f32_16x16x32_bf16 v[0:3], v[140:143], v[198:201], v[0:3]
	s_setprio 0
	s_waitcnt lgkmcnt(0)
	s_and_b64 s[4:5], s[20:21], 0x80
	s_branch .LBB0_534

; DI f32x4 mfma16(bf16x8 a, bf16x8 b, f32x4 c) { return __builtin_amdgcn_mfma_f32_16x16x32_bf16(a, b, c, 0, 0, 0); }
;     ...
;       for (int m = 0; m < MF; ++m) {
; #pragma unroll
;         for (int n = 0; n < 4; ++n) acc[m][n] = mfma16(bf[n], af[m], acc[m][n]);
.Lgp2_exit:
	s_setprio 1
	v_mfma_f32_16x16x32_bf16 v[124:127], v[202:205], v[218:221], v[124:127]
	v_mfma_f32_16x16x32_bf16 v[120:123], v[206:209], v[218:221], v[120:123]
	v_mfma_f32_16x16x32_bf16 v[116:119], v[210:213], v[218:221], v[116:119]
	v_mfma_f32_16x16x32_bf16 v[112:115], v[214:217], v[218:221], v[112:115]
	v_mfma_f32_16x16x32_bf16 v[108:111], v[202:205], v[222:225], v[108:111]
	v_mfma_f32_16x16x32_bf16 v[104:107], v[206:209], v[222:225], v[104:107]
	v_mfma_f32_16x16x32_bf16 v[100:103], v[210:213], v[222:225], v[100:103]
	v_mfma_f32_16x16x32_bf16 v[96:99], v[214:217], v[222:225], v[96:99]
	v_mfma_f32_16x16x32_bf16 v[92:95], v[202:205], v[226:229], v[92:95]
	v_mfma_f32_16x16x32_bf16 v[88:91], v[206:209], v[226:229], v[88:91]
	v_mfma_f32_16x16x32_bf16 v[84:87], v[210:213], v[226:229], v[84:87]
	v_mfma_f32_16x16x32_bf16 v[80:83], v[214:217], v[226:229], v[80:83]
	v_mfma_f32_16x16x32_bf16 v[76:79], v[202:205], v[230:233], v[76:79]
	v_mfma_f32_16x16x32_bf16 v[72:75], v[206:209], v[230:233], v[72:75]
	v_mfma_f32_16x16x32_bf16 v[68:71], v[210:213], v[230:233], v[68:71]
	v_mfma_f32_16x16x32_bf16 v[64:67], v[214:217], v[230:233], v[64:67]
	v_mfma_f32_16x16x32_bf16 v[60:63], v[202:205], v[238:241], v[60:63]
	v_mfma_f32_16x16x32_bf16 v[56:59], v[206:209], v[238:241], v[56:59]
	v_mfma_f32_16x16x32_bf16 v[52:55], v[210:213], v[238:241], v[52:55]
	v_mfma_f32_16x16x32_bf16 v[48:51], v[214:217], v[238:241], v[48:51]
	v_mfma_f32_16x16x32_bf16 v[44:47], v[202:205], v[242:245], v[44:47]
	v_mfma_f32_16x16x32_bf16 v[40:43], v[206:209], v[242:245], v[40:43]
	v_mfma_f32_16x16x32_bf16 v[36:39], v[210:213], v[242:245], v[36:39]
	v_mfma_f32_16x16x32_bf16 v[32:35], v[214:217], v[242:245], v[32:35]
	v_mfma_f32_16x16x32_bf16 v[28:31], v[202:205], v[246:249], v[28:31]
	v_mfma_f32_16x16x32_bf16 v[24:27], v[206:209], v[246:249], v[24:27]
	v_mfma_f32_16x16x32_bf16 v[20:23], v[210:213], v[246:249], v[20:23]
	v_mfma_f32_16x16x32_bf16 v[16:19], v[214:217], v[246:249], v[16:19]
	v_mfma_f32_16x16x32_bf16 v[12:15], v[202:205], v[250:253], v[12:15]
	v_mfma_f32_16x16x32_bf16 v[8:11], v[206:209], v[250:253], v[8:11]
	v_mfma_f32_16x16x32_bf16 v[4:7], v[210:213], v[250:253], v[4:7]
	v_mfma_f32_16x16x32_bf16 v[0:3], v[214:217], v[250:253], v[0:3]
	s_setprio 0
	s_nop 7
	s_nop 3
	s_branch .LBB0_551

; DI f32x4 mfma16(bf16x8 a, bf16x8 b, f32x4 c) { return __builtin_amdgcn_mfma_f32_16x16x32_bf16(a, b, c, 0, 0, 0); }
;     ...
; #pragma unroll 1
;   for (int kt = 0; kt < nk; ++kt) {
;     const bool issue = kt + 1 < nk;
;     const int ibuf = buf ^ 1;
; #pragma unroll
;     for (int s2 = 0; s2 < 2; ++s2) {
;       bf16x8 bf[4], af[MF];
;       {
;         const unsigned la = lds_base + buf * 65536 + ((wm * MF) << 11) + (s2 ? lofs1 : lofs0);
;         const unsigned lb = lds_base + buf * 65536 + 32768 + ((wn * 4) << 11) + (s2 ? lofs1 : lofs0);
;         if constexpr (MF == 8) {
;           asm volatile(
;               "ds_read_b128 %0, %13\n\tds_read_b128 %1, %13 offset:2048\n\tds_read_b128 %2, %13 offset:4096\n\tds_read_b128 %3, %13 offset:6144\n\t"
;               "ds_read_b128 %4, %12\n\tds_read_b128 %5, %12 offset:2048\n\tds_read_b128 %6, %12 offset:4096\n\tds_read_b128 %7, %12 offset:6144\n\t"
;               "ds_read_b128 %8, %12 offset:8192\n\tds_read_b128 %9, %12 offset:10240\n\tds_read_b128 %10, %12 offset:12288\n\tds_read_b128 %11, %12 offset:14336\n\t"
;               "s_waitcnt lgkmcnt(0)"
;               : "=&v"(bf[0]), "=&v"(bf[1]), "=&v"(bf[2]), "=&v"(bf[3]), "=&v"(af[0]), "=&v"(af[1]), "=&v"(af[2]), "=&v"(af[3]),
;                 "=&v"(af[4]), "=&v"(af[5]), "=&v"(af[6]), "=&v"(af[7])
;               : "v"(la), "v"(lb)
;               : "memory");
;         } else {
;           asm volatile(
;               "ds_read_b128 %0, %9\n\tds_read_b128 %1, %9 offset:2048\n\tds_read_b128 %2, %9 offset:4096\n\tds_read_b128 %3, %9 offset:6144\n\t"
;               "ds_read_b128 %4, %8\n\tds_read_b128 %5, %8 offset:2048\n\tds_read_b128 %6, %8 offset:4096\n\tds_read_b128 %7, %8 offset:6144\n\t"
;               "s_waitcnt lgkmcnt(0)"
;               : "=&v"(bf[0]), "=&v"(bf[1]), "=&v"(bf[2]), "=&v"(bf[3]), "=&v"(af[0]), "=&v"(af[1]), "=&v"(af[2]), "=&v"(af[3])
;               : "v"(la), "v"(lb)
;               : "memory");
;         }
;       }
;       __builtin_amdgcn_sched_barrier(0);
;       __builtin_amdgcn_s_setprio(1);
; #pragma unroll
;       for (int m = 0; m < MF; ++m) {
; #pragma unroll
;         for (int n = 0; n < 4; ++n) acc[m][n] = mfma16(bf[n], af[m], acc[m][n]);
;         if constexpr (MF == 8) {
;           if (m & 1) {
;             __builtin_amdgcn_sched_barrier(0);
;             if (issue) {
.LBB0_584:
	s_mov_b32 s4, s30
	s_cmp_lt_u32 s29, 43
	s_cselect_b64 s[20:21], -1, 0
	s_lshl_b32 s4, s4, 16
	v_add3_u32 v193, s4, v178, v180
	v_add3_u32 v234, s4, v179, v180
	ds_read_b128 v[128:131], v234
	ds_read_b128 v[132:135], v234 offset:2048
	ds_read_b128 v[136:139], v234 offset:4096
	ds_read_b128 v[140:143], v234 offset:6144
	ds_read_b128 v[144:147], v193
	ds_read_b128 v[148:151], v193 offset:2048
	ds_read_b128 v[152:155], v193 offset:4096
	ds_read_b128 v[156:159], v193 offset:6144
	ds_read_b128 v[160:163], v193 offset:8192
	ds_read_b128 v[164:167], v193 offset:10240
	ds_read_b128 v[194:197], v193 offset:12288
	ds_read_b128 v[198:201], v193 offset:14336
	v_add3_u32 v193, s4, v178, v181
	v_add3_u32 v234, s4, v179, v181
	s_xor_b32 s30, s30, 1
	s_lshl_b32 s5, s30, 16
	v_readfirstlane_b32 s98, v177
	s_add_u32 s98, s98, s5
	s_cmp_eq_u64 s[20:21], 0
	s_cbranch_scc1 .Lgp3_na
	s_mov_b32 m0, s98
	s_nop 0
	global_load_lds_dwordx4 v[172:173], off
	s_add_u32 m0, s98, 0x400
	v_lshl_add_u64 v[254:255], v[172:173], 0, s[14:15]
	global_load_lds_dwordx4 v[254:255], off
	s_add_u32 m0, s98, 0x800
	v_lshl_add_u64 v[254:255], v[172:173], 0, s[16:17]
	global_load_lds_dwordx4 v[254:255], off
	s_add_u32 m0, s98, 0xc00
	v_lshl_add_u64 v[254:255], v[172:173], 0, s[18:19]
	global_load_lds_dwordx4 v[254:255], off

;     ...
;   for (int kt = 0; kt < nk; ++kt) {
;     const bool issue = kt + 1 < nk;
;     const int ibuf = buf ^ 1;
; #pragma unroll
;     for (int s2 = 0; s2 < 2; ++s2) {
;       bf16x8 bf[4], af[MF];
;       {
;         const unsigned la = lds_base + buf * 65536 + ((wm * MF) << 11) + (s2 ? lofs1 : lofs0);
;         const unsigned lb = lds_base + buf * 65536 + 32768 + ((wn * 4) << 11) + (s2 ? lofs1 : lofs0);
;         if constexpr (MF == 8) {
;           asm volatile(
;               "ds_read_b128 %0, %13\n\tds_read_b128 %1, %13 offset:2048\n\tds_read_b128 %2, %13 offset:4096\n\tds_read_b128 %3, %13 offset:6144\n\t"
;               "ds_read_b128 %4, %12\n\tds_read_b128 %5, %12 offset:2048\n\tds_read_b128 %6, %12 offset:4096\n\tds_read_b128 %7, %12 offset:6144\n\t"
;               "ds_read_b128 %8, %12 offset:8192\n\tds_read_b128 %9, %12 offset:10240\n\tds_read_b128 %10, %12 offset:12288\n\tds_read_b128 %11, %12 offset:14336\n\t"
;               "s_waitcnt lgkmcnt(0)"
;               : "=&v"(bf[0]), "=&v"(bf[1]), "=&v"(bf[2]), "=&v"(bf[3]), "=&v"(af[0]), "=&v"(af[1]), "=&v"(af[2]), "=&v"(af[3]),
;                 "=&v"(af[4]), "=&v"(af[5]), "=&v"(af[6]), "=&v"(af[7])
;               : "v"(la), "v"(lb)
;               : "memory");
;         } else {
;           asm volatile(
;               "ds_read_b128 %0, %9\n\tds_read_b128 %1, %9 offset:2048\n\tds_read_b128 %2, %9 offset:4096\n\tds_read_b128 %3, %9 offset:6144\n\t"
;               "ds_read_b128 %4, %8\n\tds_read_b128 %5, %8 offset:2048\n\tds_read_b128 %6, %8 offset:4096\n\tds_read_b128 %7, %8 offset:6144\n\t"
;               "s_waitcnt lgkmcnt(0)"
;               : "=&v"(bf[0]), "=&v"(bf[1]), "=&v"(bf[2]), "=&v"(bf[3]), "=&v"(af[0]), "=&v"(af[1]), "=&v"(af[2]), "=&v"(af[3])
;               : "v"(la), "v"(lb)
;               : "memory");
;         }
;       }
;       __builtin_amdgcn_sched_barrier(0);
;       __builtin_amdgcn_s_setprio(1);
; #pragma unroll
;       for (int m = 0; m < MF; ++m) {
; #pragma unroll
;         for (int n = 0; n < 4; ++n) acc[m][n] = mfma16(bf[n], af[m], acc[m][n]);
;         if constexpr (MF == 8) {
;           if (m & 1) {
;             __builtin_amdgcn_sched_barrier(0);
;             if (issue) {
;               if (s2 == 0) { if (m == 1) GEMM_PIECE_A(ibuf, 0); if (m == 3) GEMM_PIECE_A(ibuf, 1); if (m == 5) GEMM_PIECE_A(ibuf, 2); if (m == 7) GEMM_PIECE_A(ibuf, 3); }
.Lgp3_mid:
	s_waitcnt lgkmcnt(0)
	ds_read_b128 v[202:205], v234
	ds_read_b128 v[206:209], v234 offset:2048
	ds_read_b128 v[210:213], v234 offset:4096
	ds_read_b128 v[214:217], v234 offset:6144
	ds_read_b128 v[218:221], v193
	ds_read_b128 v[222:225], v193 offset:2048
	ds_read_b128 v[226:229], v193 offset:4096
	ds_read_b128 v[230:233], v193 offset:6144
	ds_read_b128 v[238:241], v193 offset:8192
	ds_read_b128 v[242:245], v193 offset:10240
	ds_read_b128 v[246:249], v193 offset:12288
	ds_read_b128 v[250:253], v193 offset:14336
	s_cmp_eq_u64 s[20:21], 0
	s_cbranch_scc1 .Lgp3_nb
	s_add_u32 m0, s98, 0x8000
	s_nop 0
	global_load_lds_dwordx4 v[174:175], off
	s_add_u32 m0, s98, 0x8400
	v_lshl_add_u64 v[254:255], v[174:175], 0, s[14:15]
	global_load_lds_dwordx4 v[254:255], off
	s_add_u32 m0, s98, 0x8800
	v_lshl_add_u64 v[254:255], v[174:175], 0, s[16:17]
	global_load_lds_dwordx4 v[254:255], off
	s_add_u32 m0, s98, 0x8c00
	v_lshl_add_u64 v[254:255], v[174:175], 0, s[18:19]
	global_load_lds_dwordx4 v[254:255], off

; DI f32x4 mfma16(bf16x8 a, bf16x8 b, f32x4 c) { return __builtin_amdgcn_mfma_f32_16x16x32_bf16(a, b, c, 0, 0, 0); }
;     ...
; #pragma unroll 1
;   for (int kt = 0; kt < nk; ++kt) {
;     const bool issue = kt + 1 < nk;
;     const int ibuf = buf ^ 1;
; #pragma unroll
;     for (int s2 = 0; s2 < 2; ++s2) {
;       bf16x8 bf[4], af[MF];
;       {
;         const unsigned la = lds_base + buf * 65536 + ((wm * MF) << 11) + (s2 ? lofs1 : lofs0);
;         const unsigned lb = lds_base + buf * 65536 + 32768 + ((wn * 4) << 11) + (s2 ? lofs1 : lofs0);
;         if constexpr (MF == 8) {
;           asm volatile(
;               "ds_read_b128 %0, %13\n\tds_read_b128 %1, %13 offset:2048\n\tds_read_b128 %2, %13 offset:4096\n\tds_read_b128 %3, %13 offset:6144\n\t"
;               "ds_read_b128 %4, %12\n\tds_read_b128 %5, %12 offset:2048\n\tds_read_b128 %6, %12 offset:4096\n\tds_read_b128 %7, %12 offset:6144\n\t"
;               "ds_read_b128 %8, %12 offset:8192\n\tds_read_b128 %9, %12 offset:10240\n\tds_read_b128 %10, %12 offset:12288\n\tds_read_b128 %11, %12 offset:14336\n\t"
;               "s_waitcnt lgkmcnt(0)"
;               : "=&v"(bf[0]), "=&v"(bf[1]), "=&v"(bf[2]), "=&v"(bf[3]), "=&v"(af[0]), "=&v"(af[1]), "=&v"(af[2]), "=&v"(af[3]),
;                 "=&v"(af[4]), "=&v"(af[5]), "=&v"(af[6]), "=&v"(af[7])
;               : "v"(la), "v"(lb)
;               : "memory");
;         } else {
;           asm volatile(
;               "ds_read_b128 %0, %9\n\tds_read_b128 %1, %9 offset:2048\n\tds_read_b128 %2, %9 offset:4096\n\tds_read_b128 %3, %9 offset:6144\n\t"
;               "ds_read_b128 %4, %8\n\tds_read_b128 %5, %8 offset:2048\n\tds_read_b128 %6, %8 offset:4096\n\tds_read_b128 %7, %8 offset:6144\n\t"
;               "s_waitcnt lgkmcnt(0)"
;               : "=&v"(bf[0]), "=&v"(bf[1]), "=&v"(bf[2]), "=&v"(bf[3]), "=&v"(af[0]), "=&v"(af[1]), "=&v"(af[2]), "=&v"(af[3])
;               : "v"(la), "v"(lb)
;               : "memory");
;         }
;       }
;       __builtin_amdgcn_sched_barrier(0);
;       __builtin_amdgcn_s_setprio(1);
; #pragma unroll
;       for (int m = 0; m < MF; ++m) {
; #pragma unroll
;         for (int n = 0; n < 4; ++n) acc[m][n] = mfma16(bf[n], af[m], acc[m][n]);
;         if constexpr (MF == 8) {
;           if (m & 1) {
;             __builtin_amdgcn_sched_barrier(0);
;             if (issue) {
.LBB0_762:
	s_mov_b32 s2, s6
	s_cmp_lg_u32 s5, 1
	s_cselect_b64 s[0:1], -1, 0
	s_lshl_b32 s2, s2, 16
	v_add3_u32 v193, s2, v178, v180
	v_add3_u32 v234, s2, v179, v180
	ds_read_b128 v[128:131], v234
	ds_read_b128 v[132:135], v234 offset:2048
	ds_read_b128 v[136:139], v234 offset:4096
	ds_read_b128 v[140:143], v234 offset:6144
	ds_read_b128 v[144:147], v193
	ds_read_b128 v[148:151], v193 offset:2048
	ds_read_b128 v[152:155], v193 offset:4096
	ds_read_b128 v[156:159], v193 offset:6144
	ds_read_b128 v[160:163], v193 offset:8192
	ds_read_b128 v[164:167], v193 offset:10240
	ds_read_b128 v[194:197], v193 offset:12288
	ds_read_b128 v[198:201], v193 offset:14336
	v_add3_u32 v193, s2, v178, v181
	v_add3_u32 v234, s2, v179, v181
	s_xor_b32 s6, s6, 1
	s_lshl_b32 s3, s6, 16
	v_readfirstlane_b32 s98, v177
	s_add_u32 s98, s98, s3
	s_cmp_eq_u64 s[0:1], 0
	s_cbranch_scc1 .Lgp4_na
	s_mov_b32 m0, s98
	s_nop 0
	global_load_lds_dwordx4 v[172:173], off
	s_add_u32 m0, s98, 0x400
	v_lshl_add_u64 v[254:255], v[172:173], 0, s[28:29]
	global_load_lds_dwordx4 v[254:255], off
	s_add_u32 m0, s98, 0x800
	v_lshl_add_u64 v[254:255], v[172:173], 0, s[30:31]
	global_load_lds_dwordx4 v[254:255], off
	s_add_u32 m0, s98, 0xc00
	v_lshl_add_u64 v[254:255], v[172:173], 0, s[36:37]
	global_load_lds_dwordx4 v[254:255], off
.Lgp4_na:
	s_setprio 1
	v_mfma_f32_16x16x32_bf16 v[124:127], v[202:205], v[218:221], v[124:127]
	v_mfma_f32_16x16x32_bf16 v[120:123], v[206:209], v[218:221], v[120:123]
	v_mfma_f32_16x16x32_bf16 v[116:119], v[210:213], v[218:221], v[116:119]
	v_mfma_f32_16x16x32_bf16 v[112:115], v[214:217], v[218:221], v[112:115]
	v_mfma_f32_16x16x32_bf16 v[108:111], v[202:205], v[222:225], v[108:111]
	v_mfma_f32_16x16x32_bf16 v[104:107], v[206:209], v[222:225], v[104:107]
	v_mfma_f32_16x16x32_bf16 v[100:103], v[210:213], v[222:225], v[100:103]
	v_mfma_f32_16x16x32_bf16 v[96:99], v[214:217], v[222:225], v[96:99]
	v_mfma_f32_16x16x32_bf16 v[92:95], v[202:205], v[226:229], v[92:95]
	v_mfma_f32_16x16x32_bf16 v[88:91], v[206:209], v[226:229], v[88:91]
	v_mfma_f32_16x16x32_bf16 v[84:87], v[210:213], v[226:229], v[84:87]
	v_mfma_f32_16x16x32_bf16 v[80:83], v[214:217], v[226:229], v[80:83]
	v_mfma_f32_16x16x32_bf16 v[76:79], v[202:205], v[230:233], v[76:79]
	v_mfma_f32_16x16x32_bf16 v[72:75], v[206:209], v[230:233], v[72:75]
	v_mfma_f32_16x16x32_bf16 v[68:71], v[210:213], v[230:233], v[68:71]
	v_mfma_f32_16x16x32_bf16 v[64:67], v[214:217], v[230:233], v[64:67]
	v_mfma_f32_16x16x32_bf16 v[60:63], v[202:205], v[238:241], v[60:63]
	v_mfma_f32_16x16x32_bf16 v[56:59], v[206:209], v[238:241], v[56:59]
	v_mfma_f32_16x16x32_bf16 v[52:55], v[210:213], v[238:241], v[52:55]
	v_mfma_f32_16x16x32_bf16 v[48:51], v[214:217], v[238:241], v[48:51]
	v_mfma_f32_16x16x32_bf16 v[44:47], v[202:205], v[242:245], v[44:47]
	v_mfma_f32_16x16x32_bf16 v[40:43], v[206:209], v[242:245], v[40:43]
	v_mfma_f32_16x16x32_bf16 v[36:39], v[210:213], v[242:245], v[36:39]
	v_mfma_f32_16x16x32_bf16 v[32:35], v[214:217], v[242:245], v[32:35]
	v_mfma_f32_16x16x32_bf16 v[16:19], v[202:205], v[246:249], v[16:19]
	v_mfma_f32_16x16x32_bf16 v[20:23], v[206:209], v[246:249], v[20:23]
	v_mfma_f32_16x16x32_bf16 v[24:27], v[210:213], v[246:249], v[24:27]
	v_mfma_f32_16x16x32_bf16 v[28:31], v[214:217], v[246:249], v[28:31]
	v_mfma_f32_16x16x32_bf16 v[0:3], v[202:205], v[250:253], v[0:3]
	v_mfma_f32_16x16x32_bf16 v[4:7], v[206:209], v[250:253], v[4:7]
	v_mfma_f32_16x16x32_bf16 v[8:11], v[210:213], v[250:253], v[8:11]
	v_mfma_f32_16x16x32_bf16 v[12:15], v[214:217], v[250:253], v[12:15]
	s_setprio 0
.Lgp4_mid:
	s_waitcnt lgkmcnt(0)
	ds_read_b128 v[202:205], v234
	ds_read_b128 v[206:209], v234 offset:2048
	ds_read_b128 v[210:213], v234 offset:4096
	ds_read_b128 v[214:217], v234 offset:6144
	ds_read_b128 v[218:221], v193
	ds_read_b128 v[222:225], v193 offset:2048
	ds_read_b128 v[226:229], v193 offset:4096
	ds_read_b128 v[230:233], v193 offset:6144
	ds_read_b128 v[238:241], v193 offset:8192
	ds_read_b128 v[242:245], v193 offset:10240
	ds_read_b128 v[246:249], v193 offset:12288
	ds_read_b128 v[250:253], v193 offset:14336
	s_cmp_eq_u64 s[0:1], 0
	s_cbranch_scc1 .Lgp4_nb
	s_add_u32 m0, s98, 0x8000
	s_nop 0
	global_load_lds_dwordx4 v[174:175], off
	s_add_u32 m0, s98, 0x8400
	v_lshl_add_u64 v[254:255], v[174:175], 0, s[28:29]
	global_load_lds_dwordx4 v[254:255], off
	s_add_u32 m0, s98, 0x8800
	v_lshl_add_u64 v[254:255], v[174:175], 0, s[30:31]
	global_load_lds_dwordx4 v[254:255], off
	s_add_u32 m0, s98, 0x8c00
	v_lshl_add_u64 v[254:255], v[174:175], 0, s[36:37]
	global_load_lds_dwordx4 v[254:255], off
.Lgp4_nb:
	s_setprio 1
	v_mfma_f32_16x16x32_bf16 v[124:127], v[128:131], v[144:147], v[124:127]
	v_mfma_f32_16x16x32_bf16 v[120:123], v[132:135], v[144:147], v[120:123]
	v_mfma_f32_16x16x32_bf16 v[116:119], v[136:139], v[144:147], v[116:119]
	v_mfma_f32_16x16x32_bf16 v[112:115], v[140:143], v[144:147], v[112:115]
	v_mfma_f32_16x16x32_bf16 v[108:111], v[128:131], v[148:151], v[108:111]
	v_mfma_f32_16x16x32_bf16 v[104:107], v[132:135], v[148:151], v[104:107]
	v_mfma_f32_16x16x32_bf16 v[100:103], v[136:139], v[148:151], v[100:103]
	v_mfma_f32_16x16x32_bf16 v[96:99], v[140:143], v[148:151], v[96:99]
	v_mfma_f32_16x16x32_bf16 v[92:95], v[128:131], v[152:155], v[92:95]
	v_mfma_f32_16x16x32_bf16 v[88:91], v[132:135], v[152:155], v[88:91]
	v_mfma_f32_16x16x32_bf16 v[84:87], v[136:139], v[152:155], v[84:87]
	v_mfma_f32_16x16x32_bf16 v[80:83], v[140:143], v[152:155], v[80:83]
	v_mfma_f32_16x16x32_bf16 v[76:79], v[128:131], v[156:159], v[76:79]
	v_mfma_f32_16x16x32_bf16 v[72:75], v[132:135], v[156:159], v[72:75]
	v_mfma_f32_16x16x32_bf16 v[68:71], v[136:139], v[156:159], v[68:71]
	v_mfma_f32_16x16x32_bf16 v[64:67], v[140:143], v[156:159], v[64:67]
	v_mfma_f32_16x16x32_bf16 v[60:63], v[128:131], v[160:163], v[60:63]
	v_mfma_f32_16x16x32_bf16 v[56:59], v[132:135], v[160:163], v[56:59]
	v_mfma_f32_16x16x32_bf16 v[52:55], v[136:139], v[160:163], v[52:55]
	v_mfma_f32_16x16x32_bf16 v[48:51], v[140:143], v[160:163], v[48:51]
	v_mfma_f32_16x16x32_bf16 v[44:47], v[128:131], v[164:167], v[44:47]
	v_mfma_f32_16x16x32_bf16 v[40:43], v[132:135], v[164:167], v[40:43]
	v_mfma_f32_16x16x32_bf16 v[36:39], v[136:139], v[164:167], v[36:39]
	v_mfma_f32_16x16x32_bf16 v[32:35], v[140:143], v[164:167], v[32:35]
	v_mfma_f32_16x16x32_bf16 v[16:19], v[128:131], v[194:197], v[16:19]
	v_mfma_f32_16x16x32_bf16 v[20:23], v[132:135], v[194:197], v[20:23]
	v_mfma_f32_16x16x32_bf16 v[24:27], v[136:139], v[194:197], v[24:27]
	v_mfma_f32_16x16x32_bf16 v[28:31], v[140:143], v[194:197], v[28:31]
	v_mfma_f32_16x16x32_bf16 v[0:3], v[128:131], v[198:201], v[0:3]
	v_mfma_f32_16x16x32_bf16 v[4:7], v[132:135], v[198:201], v[4:7]
	v_mfma_f32_16x16x32_bf16 v[8:11], v[136:139], v[198:201], v[8:11]
	v_mfma_f32_16x16x32_bf16 v[12:15], v[140:143], v[198:201], v[12:15]
	s_setprio 0
	s_waitcnt lgkmcnt(0)
	s_and_b64 s[0:1], s[0:1], 0x80
	s_branch .LBB0_761

; DI f32x4 mfma16(bf16x8 a, bf16x8 b, f32x4 c) { return __builtin_amdgcn_mfma_f32_16x16x32_bf16(a, b, c, 0, 0, 0); }
;     ...
;       for (int m = 0; m < MF; ++m) {
; #pragma unroll
;         for (int n = 0; n < 4; ++n) acc[m][n] = mfma16(bf[n], af[m], acc[m][n]);
.Lgp4_exit:
	s_setprio 1
	v_mfma_f32_16x16x32_bf16 v[124:127], v[202:205], v[218:221], v[124:127]
	v_mfma_f32_16x16x32_bf16 v[120:123], v[206:209], v[218:221], v[120:123]
	v_mfma_f32_16x16x32_bf16 v[116:119], v[210:213], v[218:221], v[116:119]
	v_mfma_f32_16x16x32_bf16 v[112:115], v[214:217], v[218:221], v[112:115]
	v_mfma_f32_16x16x32_bf16 v[108:111], v[202:205], v[222:225], v[108:111]
	v_mfma_f32_16x16x32_bf16 v[104:107], v[206:209], v[222:225], v[104:107]
	v_mfma_f32_16x16x32_bf16 v[100:103], v[210:213], v[222:225], v[100:103]
	v_mfma_f32_16x16x32_bf16 v[96:99], v[214:217], v[222:225], v[96:99]
	v_mfma_f32_16x16x32_bf16 v[92:95], v[202:205], v[226:229], v[92:95]
	v_mfma_f32_16x16x32_bf16 v[88:91], v[206:209], v[226:229], v[88:91]
	v_mfma_f32_16x16x32_bf16 v[84:87], v[210:213], v[226:229], v[84:87]
	v_mfma_f32_16x16x32_bf16 v[80:83], v[214:217], v[226:229], v[80:83]
	v_mfma_f32_16x16x32_bf16 v[76:79], v[202:205], v[230:233], v[76:79]
	v_mfma_f32_16x16x32_bf16 v[72:75], v[206:209], v[230:233], v[72:75]
	v_mfma_f32_16x16x32_bf16 v[68:71], v[210:213], v[230:233], v[68:71]
	v_mfma_f32_16x16x32_bf16 v[64:67], v[214:217], v[230:233], v[64:67]
	v_mfma_f32_16x16x32_bf16 v[60:63], v[202:205], v[238:241], v[60:63]
	v_mfma_f32_16x16x32_bf16 v[56:59], v[206:209], v[238:241], v[56:59]
	v_mfma_f32_16x16x32_bf16 v[52:55], v[210:213], v[238:241], v[52:55]
	v_mfma_f32_16x16x32_bf16 v[48:51], v[214:217], v[238:241], v[48:51]
	v_mfma_f32_16x16x32_bf16 v[44:47], v[202:205], v[242:245], v[44:47]
	v_mfma_f32_16x16x32_bf16 v[40:43], v[206:209], v[242:245], v[40:43]
	v_mfma_f32_16x16x32_bf16 v[36:39], v[210:213], v[242:245], v[36:39]
	v_mfma_f32_16x16x32_bf16 v[32:35], v[214:217], v[242:245], v[32:35]
	v_mfma_f32_16x16x32_bf16 v[16:19], v[202:205], v[246:249], v[16:19]
	v_mfma_f32_16x16x32_bf16 v[20:23], v[206:209], v[246:249], v[20:23]
	v_mfma_f32_16x16x32_bf16 v[24:27], v[210:213], v[246:249], v[24:27]
	v_mfma_f32_16x16x32_bf16 v[28:31], v[214:217], v[246:249], v[28:31]
	v_mfma_f32_16x16x32_bf16 v[0:3], v[202:205], v[250:253], v[0:3]
	v_mfma_f32_16x16x32_bf16 v[4:7], v[206:209], v[250:253], v[4:7]
	v_mfma_f32_16x16x32_bf16 v[8:11], v[210:213], v[250:253], v[8:11]
	v_mfma_f32_16x16x32_bf16 v[12:15], v[214:217], v[250:253], v[12:15]
	s_setprio 0
	s_nop 7
	s_nop 3
	s_branch .LBB0_778

; DI f32x4 mfma16(bf16x8 a, bf16x8 b, f32x4 c) { return __builtin_amdgcn_mfma_f32_16x16x32_bf16(a, b, c, 0, 0, 0); }
;     ...
; #pragma unroll 1
;   for (int kt = 0; kt < nk; ++kt) {
;     const bool issue = kt + 1 < nk;
;     const int ibuf = buf ^ 1;
; #pragma unroll
;     for (int s2 = 0; s2 < 2; ++s2) {
;       bf16x8 bf[4], af[MF];
;       {
;         const unsigned la = lds_base + buf * 65536 + ((wm * MF) << 11) + (s2 ? lofs1 : lofs0);
;         const unsigned lb = lds_base + buf * 65536 + 32768 + ((wn * 4) << 11) + (s2 ? lofs1 : lofs0);
;         if constexpr (MF == 8) {
;           asm volatile(
;               "ds_read_b128 %0, %13\n\tds_read_b128 %1, %13 offset:2048\n\tds_read_b128 %2, %13 offset:4096\n\tds_read_b128 %3, %13 offset:6144\n\t"
;               "ds_read_b128 %4, %12\n\tds_read_b128 %5, %12 offset:2048\n\tds_read_b128 %6, %12 offset:4096\n\tds_read_b128 %7, %12 offset:6144\n\t"
;               "ds_read_b128 %8, %12 offset:8192\n\tds_read_b128 %9, %12 offset:10240\n\tds_read_b128 %10, %12 offset:12288\n\tds_read_b128 %11, %12 offset:14336\n\t"
;               "s_waitcnt lgkmcnt(0)"
;               : "=&v"(bf[0]), "=&v"(bf[1]), "=&v"(bf[2]), "=&v"(bf[3]), "=&v"(af[0]), "=&v"(af[1]), "=&v"(af[2]), "=&v"(af[3]),
;                 "=&v"(af[4]), "=&v"(af[5]), "=&v"(af[6]), "=&v"(af[7])
;               : "v"(la), "v"(lb)
;               : "memory");
;         } else {
;           asm volatile(
;               "ds_read_b128 %0, %9\n\tds_read_b128 %1, %9 offset:2048\n\tds_read_b128 %2, %9 offset:4096\n\tds_read_b128 %3, %9 offset:6144\n\t"
;               "ds_read_b128 %4, %8\n\tds_read_b128 %5, %8 offset:2048\n\tds_read_b128 %6, %8 offset:4096\n\tds_read_b128 %7, %8 offset:6144\n\t"
;               "s_waitcnt lgkmcnt(0)"
;               : "=&v"(bf[0]), "=&v"(bf[1]), "=&v"(bf[2]), "=&v"(bf[3]), "=&v"(af[0]), "=&v"(af[1]), "=&v"(af[2]), "=&v"(af[3])
;               : "v"(la), "v"(lb)
;               : "memory");
;         }
;       }
;       __builtin_amdgcn_sched_barrier(0);
;       __builtin_amdgcn_s_setprio(1);
; #pragma unroll
;       for (int m = 0; m < MF; ++m) {
; #pragma unroll
;         for (int n = 0; n < 4; ++n) acc[m][n] = mfma16(bf[n], af[m], acc[m][n]);
;         if constexpr (MF == 8) {
;           if (m & 1) {
;             __builtin_amdgcn_sched_barrier(0);
;             if (issue) {
.LBB0_839:
	s_mov_b32 s2, s59
	s_cmp_lg_u32 s58, 1
	s_cselect_b64 s[4:5], -1, 0
	s_lshl_b32 s2, s2, 16
	v_add3_u32 v193, s2, v178, v180
	v_add3_u32 v234, s2, v179, v180
	ds_read_b128 v[128:131], v234
	ds_read_b128 v[132:135], v234 offset:2048
	ds_read_b128 v[136:139], v234 offset:4096
	ds_read_b128 v[140:143], v234 offset:6144
	ds_read_b128 v[144:147], v193
	ds_read_b128 v[148:151], v193 offset:2048
	ds_read_b128 v[152:155], v193 offset:4096
	ds_read_b128 v[156:159], v193 offset:6144
	ds_read_b128 v[160:163], v193 offset:8192
	ds_read_b128 v[164:167], v193 offset:10240
	ds_read_b128 v[194:197], v193 offset:12288
	ds_read_b128 v[198:201], v193 offset:14336
	v_add3_u32 v193, s2, v178, v181
	v_add3_u32 v234, s2, v179, v181
	s_xor_b32 s59, s59, 1
	s_lshl_b32 s3, s59, 16
	v_readfirstlane_b32 s98, v177
	s_add_u32 s98, s98, s3
	s_cmp_eq_u64 s[4:5], 0
	s_cbranch_scc1 .Lgp5_na
	s_mov_b32 m0, s98
	s_nop 0
	global_load_lds_dwordx4 v[172:173], off
	s_add_u32 m0, s98, 0x400
	v_lshl_add_u64 v[254:255], v[172:173], 0, s[10:11]
	global_load_lds_dwordx4 v[254:255], off
	s_add_u32 m0, s98, 0x800
	v_lshl_add_u64 v[254:255], v[172:173], 0, s[12:13]
	global_load_lds_dwordx4 v[254:255], off
	s_add_u32 m0, s98, 0xc00
	v_lshl_add_u64 v[254:255], v[172:173], 0, s[26:27]
	global_load_lds_dwordx4 v[254:255], off

;     ...
;   for (int kt = 0; kt < nk; ++kt) {
;     const bool issue = kt + 1 < nk;
;     const int ibuf = buf ^ 1;
; #pragma unroll
;     for (int s2 = 0; s2 < 2; ++s2) {
;       bf16x8 bf[4], af[MF];
;       {
;         const unsigned la = lds_base + buf * 65536 + ((wm * MF) << 11) + (s2 ? lofs1 : lofs0);
;         const unsigned lb = lds_base + buf * 65536 + 32768 + ((wn * 4) << 11) + (s2 ? lofs1 : lofs0);
;         if constexpr (MF == 8) {
;           asm volatile(
;               "ds_read_b128 %0, %13\n\tds_read_b128 %1, %13 offset:2048\n\tds_read_b128 %2, %13 offset:4096\n\tds_read_b128 %3, %13 offset:6144\n\t"
;               "ds_read_b128 %4, %12\n\tds_read_b128 %5, %12 offset:2048\n\tds_read_b128 %6, %12 offset:4096\n\tds_read_b128 %7, %12 offset:6144\n\t"
;               "ds_read_b128 %8, %12 offset:8192\n\tds_read_b128 %9, %12 offset:10240\n\tds_read_b128 %10, %12 offset:12288\n\tds_read_b128 %11, %12 offset:14336\n\t"
;               "s_waitcnt lgkmcnt(0)"
;               : "=&v"(bf[0]), "=&v"(bf[1]), "=&v"(bf[2]), "=&v"(bf[3]), "=&v"(af[0]), "=&v"(af[1]), "=&v"(af[2]), "=&v"(af[3]),
;                 "=&v"(af[4]), "=&v"(af[5]), "=&v"(af[6]), "=&v"(af[7])
;               : "v"(la), "v"(lb)
;               : "memory");
;         } else {
;           asm volatile(
;               "ds_read_b128 %0, %9\n\tds_read_b128 %1, %9 offset:2048\n\tds_read_b128 %2, %9 offset:4096\n\tds_read_b128 %3, %9 offset:6144\n\t"
;               "ds_read_b128 %4, %8\n\tds_read_b128 %5, %8 offset:2048\n\tds_read_b128 %6, %8 offset:4096\n\tds_read_b128 %7, %8 offset:6144\n\t"
;               "s_waitcnt lgkmcnt(0)"
;               : "=&v"(bf[0]), "=&v"(bf[1]), "=&v"(bf[2]), "=&v"(bf[3]), "=&v"(af[0]), "=&v"(af[1]), "=&v"(af[2]), "=&v"(af[3])
;               : "v"(la), "v"(lb)
;               : "memory");
;         }
;       }
;       __builtin_amdgcn_sched_barrier(0);
;       __builtin_amdgcn_s_setprio(1);
; #pragma unroll
;       for (int m = 0; m < MF; ++m) {
; #pragma unroll
;         for (int n = 0; n < 4; ++n) acc[m][n] = mfma16(bf[n], af[m], acc[m][n]);
;         if constexpr (MF == 8) {
;           if (m & 1) {
;             __builtin_amdgcn_sched_barrier(0);
;             if (issue) {
;               if (s2 == 0) { if (m == 1) GEMM_PIECE_A(ibuf, 0); if (m == 3) GEMM_PIECE_A(ibuf, 1); if (m == 5) GEMM_PIECE_A(ibuf, 2); if (m == 7) GEMM_PIECE_A(ibuf, 3); }
.Lgp5_mid:
	s_waitcnt lgkmcnt(0)
	ds_read_b128 v[202:205], v234
	ds_read_b128 v[206:209], v234 offset:2048
	ds_read_b128 v[210:213], v234 offset:4096
	ds_read_b128 v[214:217], v234 offset:6144
	ds_read_b128 v[218:221], v193
	ds_read_b128 v[222:225], v193 offset:2048
	ds_read_b128 v[226:229], v193 offset:4096
	ds_read_b128 v[230:233], v193 offset:6144
	ds_read_b128 v[238:241], v193 offset:8192
	ds_read_b128 v[242:245], v193 offset:10240
	ds_read_b128 v[246:249], v193 offset:12288
	ds_read_b128 v[250:253], v193 offset:14336
	s_cmp_eq_u64 s[4:5], 0
	s_cbranch_scc1 .Lgp5_nb
	s_add_u32 m0, s98, 0x8000
	s_nop 0
	global_load_lds_dwordx4 v[174:175], off
	s_add_u32 m0, s98, 0x8400
	v_lshl_add_u64 v[254:255], v[174:175], 0, s[10:11]
	global_load_lds_dwordx4 v[254:255], off
	s_add_u32 m0, s98, 0x8800
	v_lshl_add_u64 v[254:255], v[174:175], 0, s[12:13]
	global_load_lds_dwordx4 v[254:255], off
	s_add_u32 m0, s98, 0x8c00
	v_lshl_add_u64 v[254:255], v[174:175], 0, s[26:27]
	global_load_lds_dwordx4 v[254:255], off
.Lgp5_nb:
	s_setprio 1
	v_mfma_f32_16x16x32_bf16 v[124:127], v[128:131], v[144:147], v[124:127]
	v_mfma_f32_16x16x32_bf16 v[120:123], v[132:135], v[144:147], v[120:123]
	v_mfma_f32_16x16x32_bf16 v[116:119], v[136:139], v[144:147], v[116:119]
	v_mfma_f32_16x16x32_bf16 v[112:115], v[140:143], v[144:147], v[112:115]
	v_mfma_f32_16x16x32_bf16 v[108:111], v[128:131], v[148:151], v[108:111]
	v_mfma_f32_16x16x32_bf16 v[104:107], v[132:135], v[148:151], v[104:107]
	v_mfma_f32_16x16x32_bf16 v[100:103], v[136:139], v[148:151], v[100:103]
	v_mfma_f32_16x16x32_bf16 v[96:99], v[140:143], v[148:151], v[96:99]
	v_mfma_f32_16x16x32_bf16 v[92:95], v[128:131], v[152:155], v[92:95]
	v_mfma_f32_16x16x32_bf16 v[88:91], v[132:135], v[152:155], v[88:91]
	v_mfma_f32_16x16x32_bf16 v[84:87], v[136:139], v[152:155], v[84:87]
	v_mfma_f32_16x16x32_bf16 v[80:83], v[140:143], v[152:155], v[80:83]
	v_mfma_f32_16x16x32_bf16 v[76:79], v[128:131], v[156:159], v[76:79]
	v_mfma_f32_16x16x32_bf16 v[72:75], v[132:135], v[156:159], v[72:75]
	v_mfma_f32_16x16x32_bf16 v[68:71], v[136:139], v[156:159], v[68:71]
	v_mfma_f32_16x16x32_bf16 v[64:67], v[140:143], v[156:159], v[64:67]
	v_mfma_f32_16x16x32_bf16 v[60:63], v[128:131], v[160:163], v[60:63]
	v_mfma_f32_16x16x32_bf16 v[56:59], v[132:135], v[160:163], v[56:59]
	v_mfma_f32_16x16x32_bf16 v[52:55], v[136:139], v[160:163], v[52:55]
	v_mfma_f32_16x16x32_bf16 v[48:51], v[140:143], v[160:163], v[48:51]
	v_mfma_f32_16x16x32_bf16 v[44:47], v[128:131], v[164:167], v[44:47]
	v_mfma_f32_16x16x32_bf16 v[40:43], v[132:135], v[164:167], v[40:43]
	v_mfma_f32_16x16x32_bf16 v[36:39], v[136:139], v[164:167], v[36:39]
	v_mfma_f32_16x16x32_bf16 v[32:35], v[140:143], v[164:167], v[32:35]
	v_mfma_f32_16x16x32_bf16 v[16:19], v[128:131], v[194:197], v[16:19]
	v_mfma_f32_16x16x32_bf16 v[20:23], v[132:135], v[194:197], v[20:23]
	v_mfma_f32_16x16x32_bf16 v[24:27], v[136:139], v[194:197], v[24:27]
	v_mfma_f32_16x16x32_bf16 v[28:31], v[140:143], v[194:197], v[28:31]
	v_mfma_f32_16x16x32_bf16 v[0:3], v[128:131], v[198:201], v[0:3]
	v_mfma_f32_16x16x32_bf16 v[4:7], v[132:135], v[198:201], v[4:7]
	v_mfma_f32_16x16x32_bf16 v[8:11], v[136:139], v[198:201], v[8:11]
	v_mfma_f32_16x16x32_bf16 v[12:15], v[140:143], v[198:201], v[12:15]
	s_setprio 0
	s_waitcnt lgkmcnt(0)
	s_and_b64 s[2:3], s[4:5], 0x80
	s_branch .LBB0_838

; DI u16 f2bf(float f) { return (u16)(pack2(f, 0.f) & 0xffffu); }
; __device__ __forceinline__ void scan_item(const Params& p, int stream, int h, unsigned char* smem) {
;     ...
;       float bt[4], kt[4];
; #pragma unroll
;       for (int i = 0; i < 4; ++i) {
;         const int t = 4 * tq + i;
;         const float gprev = gam;
;         gam *= sW[t * 64 + k];
;         const float ginv = frcp(gam);
;         const float av = sNKK[t * 64 + k] * gprev;
;         const float rv = sR[t * 64 + k] * gam;
;         bt[i] = sKKA[t * 64 + k] * ginv;
;         kt[i] = sKp[t * 64 + k] * ginv;
;         *(u16*)(imgA + t * 144 + k * 2) = f2bf(av);
;         *(u16*)(imgR + t * 144 + k * 2) = f2bf(rv);
;         *(u16*)(imgB + t * 144 + k * 2) = f2bf(bt[i]);
;         *(u16*)(imgK + t * 144 + k * 2) = f2bf(kt[i]);
;       }
;       u32x2 bv = {pack2(bt[0], bt[1]), pack2(bt[2], bt[3])};
;       u32x2 kv = {pack2(kt[0], kt[1]), pack2(kt[2], kt[3])};
;       *(u32x2*)(sBKT + k * 72 + tq * 8) = bv;
;       *(u32x2*)(sBKT + k * 72 + 32 + tq * 8) = kv;
;       if (tq == 3) sGam[k] = gam;
;     ...
;     {
;       const unsigned char* Limg = (wave & 1) ? imgK : imgB;
;       const unsigned char* Rimg = (wave & 2) ? imgR : imgA;
;       f32x4 d = {0.f, 0.f, 0.f, 0.f};
; #pragma unroll
;       for (int ks = 0; ks < 2; ++ks) {
;         bf16x8 lf = *(const bf16x8*)(Limg + r * 144 + ks * 64 + q * 16);
;         bf16x8 rf = *(const bf16x8*)(Rimg + r * 144 + ks * 64 + q * 16);
;         d = mfma16(lf, rf, d);
;       }
;       float x[4];
; #pragma unroll
;       for (int jj = 0; jj < 4; ++jj) {
;         const int i = 4 * q + jj;
;         const bool keep = (wave & 2) ? (i <= r) : (i < r);
;         x[jj] = keep ? d[jj] : 0.f;
;       }
;       u32x2 xv = {pack2(x[0], x[1]), pack2(x[2], x[3])};
;       *(u32x2*)(sMAT + wave * 640 + r * 40 + q * 8) = xv;
;       if (wave == 0) {
; #pragma unroll
;         for (int jj = 0; jj < 4; ++jj) sNab[(4 * q + jj) * 16 + r] = x[jj];
;       }
;     }
;     if (wave == 0) {
;       float c[16];
; #pragma unroll
;       for (int i = 0; i < 16; ++i) c[i] = (i == r) ? 1.f : 0.f;
;       int dep = 0;
; #pragma unroll
;       for (int ig = 14; ig >= 0; ig -= 2) {
;         const float* nb = sNab + dep;
; #pragma unroll
;         for (int i = ig; i > ig - 2 && i >= 0; --i) {
;           float acc0 = c[i], acc1 = 0.f;
; #pragma unroll
.LBB0_1599:
	s_or_b64 exec, exec, s[0:1]
	s_waitcnt lgkmcnt(3)
	v_cndmask_b32_e64 v72, 1.0, v72, s[10:11]
	v_mul_f32_e32 v3, v72, v3
	v_cndmask_b32_e64 v72, 1.0, v73, s[10:11]
	v_mul_f32_e32 v3, v72, v3
	s_waitcnt lgkmcnt(2)
	v_cndmask_b32_e64 v70, 1.0, v70, s[10:11]
	v_mul_f32_e32 v3, v70, v3
	v_cndmask_b32_e64 v70, 1.0, v71, s[10:11]
	v_mul_f32_e32 v3, v70, v3
	s_waitcnt lgkmcnt(1)
	v_cndmask_b32_e64 v68, 1.0, v68, s[6:7]
	v_mul_f32_e32 v3, v68, v3
	v_cndmask_b32_e64 v68, 1.0, v69, s[6:7]
	v_mul_f32_e32 v3, v68, v3
	s_waitcnt lgkmcnt(0)
	v_cndmask_b32_e64 v0, 1.0, v0, s[6:7]
	ds_read2st64_b32 v[68:69], v206 offset1:16
	v_mul_f32_e32 v3, v0, v3
	v_cndmask_b32_e64 v70, 1.0, v1, s[6:7]
	ds_read2st64_b32 v[0:1], v206 offset0:32 offset1:48
	v_mul_f32_e32 v3, v70, v3
	s_waitcnt lgkmcnt(1)
	v_mul_f32_e32 v68, v68, v3
	ds_read_b32 v71, v206 offset:16384
	v_rcp_f32_e32 v70, v68
	s_waitcnt lgkmcnt(1)
	v_mul_f32_e32 v0, v0, v3
	ds_read_b32 v3, v207 offset:16384
	ds_read_b32 v76, v208 offset:16384
	ds_read_b32 v80, v209 offset:16384
	ds_read2st64_b32 v[72:73], v207 offset1:16
	ds_read2st64_b32 v[74:75], v207 offset0:32 offset1:48
	s_waitcnt lgkmcnt(5)
	v_mul_f32_e32 v71, v71, v68
	v_cvt_pk_bf16_f32 v0, v0, s0
	ds_write_b16 v223, v0 offset:41216
	s_waitcnt lgkmcnt(2)
	v_mul_f32_e32 v77, v68, v72
	v_cvt_pk_bf16_f32 v0, v71, s0
	v_rcp_f32_e32 v71, v77
	ds_write_b16 v223, v0 offset:43520
	s_waitcnt lgkmcnt(2)
	v_mul_f32_e32 v0, v68, v74
	v_mov_b32_e32 v74, v1
	v_pk_mul_f32 v[74:75], v[74:75], v[70:71]
	v_mov_b32_e32 v72, v69
	v_cvt_pk_bf16_f32 v1, v74, s0
	v_pk_mul_f32 v[68:69], v[72:73], v[70:71]
	v_mul_f32_e32 v3, v77, v3
	ds_write_b16 v223, v1 offset:45824
	v_cvt_pk_bf16_f32 v1, v68, s0
	v_cvt_pk_bf16_f32 v0, v0, s0
	ds_write_b16 v223, v1 offset:48128
	ds_write_b16 v224, v0 offset:41216
	v_cvt_pk_bf16_f32 v0, v3, s0
	ds_write_b16 v224, v0 offset:43520
	ds_read2st64_b32 v[0:1], v208 offset1:16
	ds_read2st64_b32 v[70:71], v208 offset0:32 offset1:48
	v_cvt_pk_bf16_f32 v3, v75, s0
	ds_write_b16 v224, v3 offset:45824
	v_cvt_pk_bf16_f32 v3, v69, s0
	ds_write_b16 v224, v3 offset:48128
	s_waitcnt lgkmcnt(3)
	v_mul_f32_e32 v3, v77, v0
	s_waitcnt lgkmcnt(2)
	v_mul_f32_e32 v0, v77, v70
	v_mul_f32_e32 v70, v3, v76
	ds_read2st64_b32 v[76:77], v209 offset1:16
	v_cvt_pk_bf16_f32 v0, v0, s0
	ds_write_b16 v224, v0 offset:41360
	ds_read2st64_b32 v[78:79], v209 offset0:32 offset1:48
	v_cvt_pk_bf16_f32 v0, v70, s0
	ds_write_b16 v224, v0 offset:43664
	s_waitcnt lgkmcnt(3)
	v_mul_f32_e32 v0, v3, v76
	v_rcp_f32_e32 v72, v3
	v_rcp_f32_e32 v73, v0
	s_waitcnt lgkmcnt(1)
	v_mul_f32_e32 v3, v3, v78
	v_mov_b32_e32 v78, v71
	v_mul_f32_e32 v80, v0, v80
	v_pk_mul_f32 v[70:71], v[72:73], v[78:79]
	v_cvt_pk_bf16_f32 v74, v74, v75
	v_cvt_pk_bf16_f32 v76, v70, s0
	ds_write_b16 v224, v76 offset:45968
	v_mov_b32_e32 v76, v1
	v_pk_mul_f32 v[72:73], v[72:73], v[76:77]
	v_cvt_pk_bf16_f32 v75, v70, v71
	v_cvt_pk_bf16_f32 v1, v72, s0
	ds_write_b16 v224, v1 offset:48272
	v_cvt_pk_bf16_f32 v1, v3, s0
	ds_write_b16 v224, v1 offset:41504
	v_cvt_pk_bf16_f32 v1, v80, s0
	ds_write_b16 v224, v1 offset:43808
	v_cvt_pk_bf16_f32 v1, v71, s0
	ds_write_b16 v224, v1 offset:46112
	v_cvt_pk_bf16_f32 v1, v73, s0
	v_cvt_pk_bf16_f32 v68, v68, v69
	v_cvt_pk_bf16_f32 v69, v72, v73
	ds_write_b16 v224, v1 offset:48416
	ds_write2_b64 v230, v[74:75], v[68:69] offset0:160 offset1:164
	s_and_saveexec_b64 s[0:1], s[6:7]
	ds_write_b32 v225, v0 offset:58624
	s_or_b64 exec, exec, s[0:1]
	s_waitcnt lgkmcnt(0)
	s_barrier
	ds_read_b128 v[68:71], v226
	ds_read_b128 v[72:75], v227
	s_waitcnt lgkmcnt(0)
	v_mfma_f32_16x16x32_bf16 v[68:71], v[68:71], v[72:75], 0
	ds_read_b128 v[72:75], v226 offset:64
	ds_read_b128 v[76:79], v227 offset:64
	s_waitcnt lgkmcnt(0)
	v_mfma_f32_16x16x32_bf16 v[68:71], v[72:75], v[76:79], v[68:71]
	s_nop 7
	v_cndmask_b32_e64 v0, 0, v68, s[12:13]
	v_cndmask_b32_e64 v1, 0, v69, s[14:15]
	v_cndmask_b32_e64 v3, 0, v70, s[16:17]
	v_cndmask_b32_e64 v68, 0, v71, s[18:19]
	v_cvt_pk_bf16_f32 v70, v0, v1
	v_cvt_pk_bf16_f32 v71, v3, v68
	ds_write_b64 v228, v[70:71] offset:55040
	s_and_saveexec_b64 s[0:1], s[56:57]
	s_cbranch_execz .LBB0_1603
	v_add_u32_e32 v69, 0xe000, v229
	ds_write2_b32 v69, v0, v1 offset0:64 offset1:80
	ds_write2_b32 v69, v3, v68 offset0:96 offset1:112
	ds_read_b32 v238, v195 offset:58556
	ds_read_b64 v[240:241], v195 offset:58488
	ds_read_b32 v242, v195 offset:58420
	ds_read_b64 v[244:245], v195 offset:58424
	ds_read_b64 v[246:247], v195 offset:58352
	ds_read_b64 v[248:249], v195 offset:58360
	ds_read_b32 v250, v195 offset:58284
	ds_read_b64 v[252:253], v195 offset:58288
	s_waitcnt lgkmcnt(7)
	v_fma_f32 v150, v151, v238, v216
	ds_read_b64 v[254:255], v195 offset:58296
	v_mul_f32_e32 v152, v130, v150
	s_waitcnt lgkmcnt(7)
	v_pk_fma_f32 v[0:1], v[150:151], v[240:241], v[148:149]
	ds_read_b64 v[238:239], v195 offset:58216
	s_nop 0
	v_pk_add_f32 v[68:69], v[0:1], v[0:1] op_sel:[1,0] op_sel_hi:[0,1]
	s_nop 0
	s_waitcnt lgkmcnt(7)
	v_fma_f32 v3, v242, v68, v215
	ds_read_b64 v[240:241], v195 offset:58224
	s_waitcnt lgkmcnt(7)
	v_pk_fma_f32 v[0:1], v[150:151], v[244:245], v[2:3]
	ds_read_b64 v[242:243], v195 offset:58232
	s_nop 0
	v_pk_add_f32 v[0:1], v[0:1], v[0:1] op_sel:[0,1] op_sel_hi:[1,0]
	v_mov_b32_e32 v1, v68
	s_waitcnt lgkmcnt(7)
	v_pk_fma_f32 v[68:69], v[0:1], v[246:247], v[146:147]
	ds_read_b32 v244, v195 offset:58148
	s_waitcnt lgkmcnt(7)
	v_pk_fma_f32 v[68:69], v[150:151], v[248:249], v[68:69]
	ds_read_b64 v[246:247], v195 offset:58152
	s_nop 0
	v_pk_add_f32 v[70:71], v[68:69], v[68:69] op_sel:[1,0] op_sel_hi:[0,1]
	s_nop 0
	s_waitcnt lgkmcnt(7)
; __device__ __forceinline__ void scan_item(const Params& p, int stream, int h, unsigned char* smem) {
;     ...
; #pragma unroll
;       for (int ig = 14; ig >= 0; ig -= 2) {
;         const float* nb = sNab + dep;
; #pragma unroll
;         for (int i = ig; i > ig - 2 && i >= 0; --i) {
;           float acc0 = c[i], acc1 = 0.f;
; #pragma unroll
;           for (int j = i + 1; j < 16; ++j) { if ((j - i) & 1) acc0 += nb[i * 16 + j] * c[j]; else acc1 += nb[i * 16 + j] * c[j]; }
;           c[i] = acc0 + acc1;
;         }
;         asm volatile("v_mov_b32 %0, 0" : "=v"(dep) : "v"(c[ig > 0 ? ig - 1 : 0]));
	v_fma_f32 v3, v250, v70, v214
	ds_read_b64 v[248:249], v195 offset:58160
	s_waitcnt lgkmcnt(7)
	v_pk_fma_f32 v[68:69], v[0:1], v[252:253], v[2:3]
	ds_read_b64 v[250:251], v195 offset:58168
	s_waitcnt lgkmcnt(7)
	v_pk_fma_f32 v[68:69], v[150:151], v[254:255], v[68:69]
	ds_read_b64 v[252:253], v195 offset:58080
	v_pk_add_f32 v[68:69], v[68:69], v[68:69] op_sel:[0,1] op_sel_hi:[1,0]
	v_mov_b32_e32 v69, v70
	s_waitcnt lgkmcnt(7)
	v_pk_fma_f32 v[70:71], v[238:239], v[68:69], v[144:145]
	ds_read_b64 v[254:255], v195 offset:58088
	s_waitcnt lgkmcnt(7)
	v_pk_fma_f32 v[70:71], v[0:1], v[240:241], v[70:71]
	ds_read_b64 v[238:239], v195 offset:58096
	s_waitcnt lgkmcnt(7)
	v_pk_fma_f32 v[70:71], v[150:151], v[242:243], v[70:71]
	ds_read_b64 v[240:241], v195 offset:58104
	s_nop 0
	v_pk_add_f32 v[72:73], v[70:71], v[70:71] op_sel:[0,1] op_sel_hi:[1,0]
	s_nop 0
	s_nop 0
	s_waitcnt lgkmcnt(7)
	v_fma_f32 v3, v244, v72, v213
	ds_read_b32 v242, v195 offset:58012
	s_waitcnt lgkmcnt(7)
	v_pk_fma_f32 v[70:71], v[68:69], v[246:247], v[2:3]
	ds_read_b64 v[244:245], v195 offset:58016
	s_waitcnt lgkmcnt(7)
	v_pk_fma_f32 v[70:71], v[0:1], v[248:249], v[70:71]
	ds_read_b64 v[246:247], v195 offset:58024
	s_waitcnt lgkmcnt(7)
	v_pk_fma_f32 v[70:71], v[150:151], v[250:251], v[70:71]
	ds_read_b64 v[248:249], v195 offset:58032
	v_pk_add_f32 v[70:71], v[70:71], v[70:71] op_sel:[0,1] op_sel_hi:[1,0]
	v_mov_b32_e32 v71, v72
	s_waitcnt lgkmcnt(7)
	v_pk_fma_f32 v[72:73], v[252:253], v[70:71], v[142:143]
	ds_read_b64 v[250:251], v195 offset:58040
	s_waitcnt lgkmcnt(7)
	v_pk_fma_f32 v[72:73], v[68:69], v[254:255], v[72:73]
	ds_read_b64 v[252:253], v195 offset:57944
	s_waitcnt lgkmcnt(7)
	v_pk_fma_f32 v[72:73], v[0:1], v[238:239], v[72:73]
	ds_read_b64 v[254:255], v195 offset:57952
	s_waitcnt lgkmcnt(7)
	v_pk_fma_f32 v[72:73], v[150:151], v[240:241], v[72:73]
	ds_read_b64 v[238:239], v195 offset:57960
	s_nop 0
	v_pk_add_f32 v[72:73], v[72:73], v[72:73] op_sel:[0,1] op_sel_hi:[1,0]
	s_nop 0
	s_nop 0
	s_waitcnt lgkmcnt(7)
	v_fma_f32 v3, v242, v72, v212
	ds_read_b64 v[240:241], v195 offset:57968
	s_waitcnt lgkmcnt(7)
	v_pk_fma_f32 v[74:75], v[70:71], v[244:245], v[2:3]
	ds_read_b64 v[242:243], v195 offset:57976
	s_waitcnt lgkmcnt(7)
	v_pk_fma_f32 v[74:75], v[68:69], v[246:247], v[74:75]
	ds_read_b32 v244, v195 offset:57876
	s_waitcnt lgkmcnt(7)
	v_pk_fma_f32 v[74:75], v[0:1], v[248:249], v[74:75]
	ds_read_b64 v[246:247], v195 offset:57880
	s_waitcnt lgkmcnt(7)
	v_pk_fma_f32 v[74:75], v[150:151], v[250:251], v[74:75]
	ds_read_b64 v[248:249], v195 offset:57888
	v_pk_add_f32 v[74:75], v[74:75], v[74:75] op_sel:[0,1] op_sel_hi:[1,0]
	v_mov_b32_e32 v75, v72
	s_waitcnt lgkmcnt(7)
	v_pk_fma_f32 v[76:77], v[252:253], v[74:75], v[140:141]
	ds_read_b64 v[250:251], v195 offset:57896
	s_waitcnt lgkmcnt(7)
	v_pk_fma_f32 v[76:77], v[70:71], v[254:255], v[76:77]
	ds_read_b64 v[252:253], v195 offset:57904
	s_waitcnt lgkmcnt(7)
	v_pk_fma_f32 v[76:77], v[68:69], v[238:239], v[76:77]
	ds_read_b64 v[254:255], v195 offset:57912
	s_waitcnt lgkmcnt(7)
	v_pk_fma_f32 v[76:77], v[0:1], v[240:241], v[76:77]
	ds_read_b64 v[238:239], v195 offset:57808
	s_waitcnt lgkmcnt(7)
	v_pk_fma_f32 v[76:77], v[150:151], v[242:243], v[76:77]
	ds_read_b64 v[240:241], v195 offset:57816
	s_nop 0
	v_pk_add_f32 v[76:77], v[76:77], v[76:77] op_sel:[0,1] op_sel_hi:[1,0]
	s_nop 0
	s_nop 0
	s_waitcnt lgkmcnt(7)
	v_fma_f32 v3, v244, v76, v211
	ds_read_b64 v[242:243], v195 offset:57824
	s_waitcnt lgkmcnt(7)
	v_pk_fma_f32 v[78:79], v[74:75], v[246:247], v[2:3]
	ds_read_b64 v[244:245], v195 offset:57832
	s_waitcnt lgkmcnt(7)
	v_pk_fma_f32 v[78:79], v[70:71], v[248:249], v[78:79]
	ds_read_b64 v[246:247], v195 offset:57840
	s_waitcnt lgkmcnt(7)
	v_pk_fma_f32 v[78:79], v[68:69], v[250:251], v[78:79]
	ds_read_b64 v[248:249], v195 offset:57848
	s_waitcnt lgkmcnt(7)
	v_pk_fma_f32 v[78:79], v[0:1], v[252:253], v[78:79]
	ds_read_b32 v250, v195 offset:57740
	s_waitcnt lgkmcnt(7)
	v_pk_fma_f32 v[78:79], v[150:151], v[254:255], v[78:79]
	ds_read_b64 v[252:253], v195 offset:57744
	v_pk_add_f32 v[78:79], v[78:79], v[78:79] op_sel:[0,1] op_sel_hi:[1,0]
	v_mov_b32_e32 v79, v76
	s_waitcnt lgkmcnt(7)
; __device__ __forceinline__ void scan_item(const Params& p, int stream, int h, unsigned char* smem) {
;     ...
; #pragma unroll
;       for (int ig = 14; ig >= 0; ig -= 2) {
;         const float* nb = sNab + dep;
; #pragma unroll
;         for (int i = ig; i > ig - 2 && i >= 0; --i) {
;           float acc0 = c[i], acc1 = 0.f;
; #pragma unroll
;           for (int j = i + 1; j < 16; ++j) { if ((j - i) & 1) acc0 += nb[i * 16 + j] * c[j]; else acc1 += nb[i * 16 + j] * c[j]; }
;           c[i] = acc0 + acc1;
;         }
;         asm volatile("v_mov_b32 %0, 0" : "=v"(dep) : "v"(c[ig > 0 ? ig - 1 : 0]));
;       }
;       float tc[4];
;       const float qm0 = q == 0 ? 1.f : 0.f, qm1 = q == 1 ? 1.f : 0.f, qm2 = q == 2 ? 1.f : 0.f, qm3 = q == 3 ? 1.f : 0.f;
; #pragma unroll
;       for (int e = 0; e < 4; ++e) tc[e] = qm0 * c[e] + qm1 * c[4 + e] + qm2 * c[8 + e] + qm3 * c[12 + e];
;       { u32x2 tv = {pack2(tc[0], tc[1]), pack2(tc[2], tc[3])}; *(u32x2*)(sTT + r * 40 + q * 8) = tv; }
	v_pk_fma_f32 v[80:81], v[238:239], v[78:79], v[138:139]
	ds_read_b64 v[254:255], v195 offset:57752
	s_waitcnt lgkmcnt(7)
	v_pk_fma_f32 v[80:81], v[74:75], v[240:241], v[80:81]
	ds_read_b64 v[238:239], v195 offset:57760
	s_waitcnt lgkmcnt(7)
	v_pk_fma_f32 v[80:81], v[70:71], v[242:243], v[80:81]
	ds_read_b64 v[240:241], v195 offset:57768
	s_waitcnt lgkmcnt(7)
	v_pk_fma_f32 v[80:81], v[68:69], v[244:245], v[80:81]
	ds_read_b64 v[242:243], v195 offset:57776
	s_waitcnt lgkmcnt(7)
	v_pk_fma_f32 v[80:81], v[0:1], v[246:247], v[80:81]
	ds_read_b64 v[244:245], v195 offset:57784
	s_waitcnt lgkmcnt(7)
	v_pk_fma_f32 v[80:81], v[150:151], v[248:249], v[80:81]
	ds_read_b64 v[246:247], v195 offset:57672
	s_nop 0
	v_pk_add_f32 v[80:81], v[80:81], v[80:81] op_sel:[0,1] op_sel_hi:[1,0]
	s_nop 0
	s_nop 0
	s_waitcnt lgkmcnt(7)
	v_fma_f32 v3, v250, v80, v210
	ds_read_b64 v[248:249], v195 offset:57680
	s_waitcnt lgkmcnt(7)
	v_pk_fma_f32 v[82:83], v[78:79], v[252:253], v[2:3]
	ds_read_b64 v[250:251], v195 offset:57688
	s_waitcnt lgkmcnt(7)
	v_pk_fma_f32 v[82:83], v[74:75], v[254:255], v[82:83]
	ds_read_b64 v[252:253], v195 offset:57696
	s_waitcnt lgkmcnt(7)
	v_pk_fma_f32 v[82:83], v[70:71], v[238:239], v[82:83]
	ds_read_b64 v[254:255], v195 offset:57704
	s_waitcnt lgkmcnt(7)
	v_pk_fma_f32 v[82:83], v[68:69], v[240:241], v[82:83]
	ds_read_b64 v[238:239], v195 offset:57712
	s_waitcnt lgkmcnt(7)
	v_pk_fma_f32 v[82:83], v[0:1], v[242:243], v[82:83]
	ds_read_b64 v[240:241], v195 offset:57720
	s_waitcnt lgkmcnt(7)
	v_pk_fma_f32 v[82:83], v[150:151], v[244:245], v[82:83]
	ds_read_b32 v242, v195 offset:57604
	v_pk_add_f32 v[82:83], v[82:83], v[82:83] op_sel:[0,1] op_sel_hi:[1,0]
	v_mov_b32_e32 v83, v80
	s_waitcnt lgkmcnt(7)
	v_pk_fma_f32 v[84:85], v[246:247], v[82:83], v[136:137]
	ds_read_b64 v[244:245], v195 offset:57608
	s_waitcnt lgkmcnt(7)
	v_pk_fma_f32 v[84:85], v[78:79], v[248:249], v[84:85]
	ds_read_b64 v[246:247], v195 offset:57616
	s_waitcnt lgkmcnt(7)
	v_pk_fma_f32 v[84:85], v[74:75], v[250:251], v[84:85]
	ds_read_b64 v[248:249], v195 offset:57624
	s_waitcnt lgkmcnt(7)
	v_pk_fma_f32 v[84:85], v[70:71], v[252:253], v[84:85]
	ds_read_b64 v[250:251], v195 offset:57632
	s_waitcnt lgkmcnt(7)
	v_pk_fma_f32 v[84:85], v[68:69], v[254:255], v[84:85]
	ds_read_b64 v[252:253], v195 offset:57640
	s_waitcnt lgkmcnt(7)
	v_pk_fma_f32 v[84:85], v[0:1], v[238:239], v[84:85]
	ds_read_b64 v[254:255], v195 offset:57648
	s_waitcnt lgkmcnt(7)
	v_pk_fma_f32 v[84:85], v[150:151], v[240:241], v[84:85]
	ds_read_b64 v[238:239], v195 offset:57656
	s_nop 0
	v_pk_add_f32 v[84:85], v[84:85], v[84:85] op_sel:[0,1] op_sel_hi:[1,0]
	s_nop 0
	s_nop 0
	s_waitcnt lgkmcnt(7)
	v_fma_f32 v3, v242, v84, v217
	s_waitcnt lgkmcnt(6)
	v_pk_fma_f32 v[86:87], v[82:83], v[244:245], v[2:3]
	v_mov_b32_e32 v83, v72
	s_waitcnt lgkmcnt(5)
	v_pk_fma_f32 v[86:87], v[78:79], v[246:247], v[86:87]
	v_mov_b32_e32 v79, v84
	v_pk_mul_f32 v[78:79], v[164:165], v[78:79]
	s_waitcnt lgkmcnt(4)
	v_pk_fma_f32 v[86:87], v[74:75], v[248:249], v[86:87]
	v_mov_b32_e32 v75, v80
	s_waitcnt lgkmcnt(3)
	v_pk_fma_f32 v[86:87], v[70:71], v[250:251], v[86:87]
	s_waitcnt lgkmcnt(2)
	v_pk_fma_f32 v[86:87], v[68:69], v[252:253], v[86:87]
	s_waitcnt lgkmcnt(1)
	v_pk_fma_f32 v[86:87], v[0:1], v[254:255], v[86:87]
	s_waitcnt lgkmcnt(0)
	v_pk_fma_f32 v[86:87], v[150:151], v[238:239], v[86:87]
	s_nop 0
	v_pk_add_f32 v[86:87], v[86:87], v[86:87] op_sel:[0,1] op_sel_hi:[1,0]
	s_nop 0
	v_mov_b32_e32 v87, v76
	v_pk_fma_f32 v[76:77], v[126:127], v[86:87], v[78:79]
	s_nop 0
	v_pk_fma_f32 v[70:71], v[128:129], v[70:71], v[76:77]
	v_add_u32_e32 v3, v202, v95
	v_pk_fma_f32 v[0:1], v[130:131], v[0:1], v[70:71]
	v_pk_mul_f32 v[70:71], v[164:165], v[74:75]
	v_cvt_pk_bf16_f32 v0, v0, v1
	v_pk_fma_f32 v[70:71], v[126:127], v[82:83], v[70:71]
	s_nop 0
	v_pk_fma_f32 v[68:69], v[128:129], v[68:69], v[70:71]
	s_nop 0
	v_pk_add_f32 v[68:69], v[152:153], v[68:69]
	s_nop 0
	v_cvt_pk_bf16_f32 v1, v68, v69
	ds_write_b64 v3, v[0:1] offset:58880

; DI f32x4 mfma16(bf16x8 a, bf16x8 b, f32x4 c) { return __builtin_amdgcn_mfma_f32_16x16x32_bf16(a, b, c, 0, 0, 0); }
;     ...
; #pragma unroll 1
;   for (int kt = 0; kt < nk; ++kt) {
;     const bool issue = kt + 1 < nk;
;     const int ibuf = buf ^ 1;
; #pragma unroll
;     for (int s2 = 0; s2 < 2; ++s2) {
;       bf16x8 bf[4], af[MF];
;       {
;         const unsigned la = lds_base + buf * 65536 + ((wm * MF) << 11) + (s2 ? lofs1 : lofs0);
;         const unsigned lb = lds_base + buf * 65536 + 32768 + ((wn * 4) << 11) + (s2 ? lofs1 : lofs0);
;         if constexpr (MF == 8) {
;           asm volatile(
;               "ds_read_b128 %0, %13\n\tds_read_b128 %1, %13 offset:2048\n\tds_read_b128 %2, %13 offset:4096\n\tds_read_b128 %3, %13 offset:6144\n\t"
;               "ds_read_b128 %4, %12\n\tds_read_b128 %5, %12 offset:2048\n\tds_read_b128 %6, %12 offset:4096\n\tds_read_b128 %7, %12 offset:6144\n\t"
;               "ds_read_b128 %8, %12 offset:8192\n\tds_read_b128 %9, %12 offset:10240\n\tds_read_b128 %10, %12 offset:12288\n\tds_read_b128 %11, %12 offset:14336\n\t"
;               "s_waitcnt lgkmcnt(0)"
;               : "=&v"(bf[0]), "=&v"(bf[1]), "=&v"(bf[2]), "=&v"(bf[3]), "=&v"(af[0]), "=&v"(af[1]), "=&v"(af[2]), "=&v"(af[3]),
;                 "=&v"(af[4]), "=&v"(af[5]), "=&v"(af[6]), "=&v"(af[7])
;               : "v"(la), "v"(lb)
;               : "memory");
;         } else {
;           asm volatile(
;               "ds_read_b128 %0, %9\n\tds_read_b128 %1, %9 offset:2048\n\tds_read_b128 %2, %9 offset:4096\n\tds_read_b128 %3, %9 offset:6144\n\t"
;               "ds_read_b128 %4, %8\n\tds_read_b128 %5, %8 offset:2048\n\tds_read_b128 %6, %8 offset:4096\n\tds_read_b128 %7, %8 offset:6144\n\t"
;               "s_waitcnt lgkmcnt(0)"
;               : "=&v"(bf[0]), "=&v"(bf[1]), "=&v"(bf[2]), "=&v"(bf[3]), "=&v"(af[0]), "=&v"(af[1]), "=&v"(af[2]), "=&v"(af[3])
;               : "v"(la), "v"(lb)
;               : "memory");
;         }
;       }
;       __builtin_amdgcn_sched_barrier(0);
;       __builtin_amdgcn_s_setprio(1);
; #pragma unroll
;       for (int m = 0; m < MF; ++m) {
; #pragma unroll
;         for (int n = 0; n < 4; ++n) acc[m][n] = mfma16(bf[n], af[m], acc[m][n]);
;         if constexpr (MF == 8) {
;           if (m & 1) {
;             __builtin_amdgcn_sched_barrier(0);
;             if (issue) {
.LBB0_1675:
	s_mov_b32 s4, s28
	s_cmp_lt_u32 s27, 15
	s_cselect_b64 s[22:23], -1, 0
	s_lshl_b32 s4, s4, 16
	v_add3_u32 v195, s4, v168, v181
	v_add3_u32 v236, s4, v180, v181
	ds_read_b128 v[128:131], v236
	ds_read_b128 v[132:135], v236 offset:2048
	ds_read_b128 v[136:139], v236 offset:4096
	ds_read_b128 v[140:143], v236 offset:6144
	ds_read_b128 v[144:147], v195
	ds_read_b128 v[148:151], v195 offset:2048
	ds_read_b128 v[152:155], v195 offset:4096
	ds_read_b128 v[156:159], v195 offset:6144
	ds_read_b128 v[160:163], v195 offset:8192
	ds_read_b128 v[164:167], v195 offset:10240
	ds_read_b128 v[196:199], v195 offset:12288
	ds_read_b128 v[200:203], v195 offset:14336
	v_add3_u32 v195, s4, v168, v182
	v_add3_u32 v236, s4, v180, v182
	s_xor_b32 s28, s28, 1
	s_lshl_b32 s5, s28, 16
	v_readfirstlane_b32 s98, v179
	s_add_u32 s98, s98, s5
	s_cmp_eq_u64 s[22:23], 0
	s_cbranch_scc1 .Lgp7_na
	s_mov_b32 m0, s98
	s_nop 0
	global_load_lds_dwordx4 v[174:175], off
	s_add_u32 m0, s98, 0x400
	v_lshl_add_u64 v[254:255], v[174:175], 0, s[14:15]
	global_load_lds_dwordx4 v[254:255], off
	s_add_u32 m0, s98, 0x800
	v_lshl_add_u64 v[254:255], v[174:175], 0, s[16:17]
	global_load_lds_dwordx4 v[254:255], off
	s_add_u32 m0, s98, 0xc00
	v_lshl_add_u64 v[254:255], v[174:175], 0, s[18:19]
	global_load_lds_dwordx4 v[254:255], off
.Lgp7_na:
	s_setprio 1
	v_mfma_f32_16x16x32_bf16 v[124:127], v[204:207], v[220:223], v[124:127]
	v_mfma_f32_16x16x32_bf16 v[120:123], v[208:211], v[220:223], v[120:123]
	v_mfma_f32_16x16x32_bf16 v[116:119], v[212:215], v[220:223], v[116:119]
	v_mfma_f32_16x16x32_bf16 v[112:115], v[216:219], v[220:223], v[112:115]
	v_mfma_f32_16x16x32_bf16 v[108:111], v[204:207], v[224:227], v[108:111]
	v_mfma_f32_16x16x32_bf16 v[104:107], v[208:211], v[224:227], v[104:107]
	v_mfma_f32_16x16x32_bf16 v[100:103], v[212:215], v[224:227], v[100:103]
	v_mfma_f32_16x16x32_bf16 v[96:99], v[216:219], v[224:227], v[96:99]
	v_mfma_f32_16x16x32_bf16 v[92:95], v[204:207], v[228:231], v[92:95]
	v_mfma_f32_16x16x32_bf16 v[88:91], v[208:211], v[228:231], v[88:91]
	v_mfma_f32_16x16x32_bf16 v[84:87], v[212:215], v[228:231], v[84:87]
	v_mfma_f32_16x16x32_bf16 v[80:83], v[216:219], v[228:231], v[80:83]
	v_mfma_f32_16x16x32_bf16 v[76:79], v[204:207], v[232:235], v[76:79]
	v_mfma_f32_16x16x32_bf16 v[72:75], v[208:211], v[232:235], v[72:75]
	v_mfma_f32_16x16x32_bf16 v[68:71], v[212:215], v[232:235], v[68:71]
	v_mfma_f32_16x16x32_bf16 v[64:67], v[216:219], v[232:235], v[64:67]
	v_mfma_f32_16x16x32_bf16 v[60:63], v[204:207], v[238:241], v[60:63]
	v_mfma_f32_16x16x32_bf16 v[56:59], v[208:211], v[238:241], v[56:59]
	v_mfma_f32_16x16x32_bf16 v[52:55], v[212:215], v[238:241], v[52:55]
	v_mfma_f32_16x16x32_bf16 v[48:51], v[216:219], v[238:241], v[48:51]
	v_mfma_f32_16x16x32_bf16 v[44:47], v[204:207], v[242:245], v[44:47]
	v_mfma_f32_16x16x32_bf16 v[40:43], v[208:211], v[242:245], v[40:43]
	v_mfma_f32_16x16x32_bf16 v[36:39], v[212:215], v[242:245], v[36:39]
	v_mfma_f32_16x16x32_bf16 v[32:35], v[216:219], v[242:245], v[32:35]
	v_mfma_f32_16x16x32_bf16 v[28:31], v[204:207], v[246:249], v[28:31]
	v_mfma_f32_16x16x32_bf16 v[24:27], v[208:211], v[246:249], v[24:27]
	v_mfma_f32_16x16x32_bf16 v[20:23], v[212:215], v[246:249], v[20:23]
	v_mfma_f32_16x16x32_bf16 v[16:19], v[216:219], v[246:249], v[16:19]
	v_mfma_f32_16x16x32_bf16 v[12:15], v[204:207], v[250:253], v[12:15]
	v_mfma_f32_16x16x32_bf16 v[8:11], v[208:211], v[250:253], v[8:11]
	v_mfma_f32_16x16x32_bf16 v[4:7], v[212:215], v[250:253], v[4:7]
	v_mfma_f32_16x16x32_bf16 v[0:3], v[216:219], v[250:253], v[0:3]
	s_setprio 0
.Lgp7_mid:
	s_waitcnt lgkmcnt(0)
	ds_read_b128 v[204:207], v236
	ds_read_b128 v[208:211], v236 offset:2048
	ds_read_b128 v[212:215], v236 offset:4096
	ds_read_b128 v[216:219], v236 offset:6144
	ds_read_b128 v[220:223], v195
	ds_read_b128 v[224:227], v195 offset:2048
	ds_read_b128 v[228:231], v195 offset:4096
	ds_read_b128 v[232:235], v195 offset:6144
	ds_read_b128 v[238:241], v195 offset:8192
	ds_read_b128 v[242:245], v195 offset:10240
	ds_read_b128 v[246:249], v195 offset:12288
	ds_read_b128 v[250:253], v195 offset:14336
	s_cmp_eq_u64 s[22:23], 0
	s_cbranch_scc1 .Lgp7_nb
	s_add_u32 m0, s98, 0x8000
	s_nop 0
	global_load_lds_dwordx4 v[176:177], off
	s_add_u32 m0, s98, 0x8400
	v_lshl_add_u64 v[254:255], v[176:177], 0, s[14:15]
	global_load_lds_dwordx4 v[254:255], off
	s_add_u32 m0, s98, 0x8800
	v_lshl_add_u64 v[254:255], v[176:177], 0, s[16:17]
	global_load_lds_dwordx4 v[254:255], off
	s_add_u32 m0, s98, 0x8c00
	v_lshl_add_u64 v[254:255], v[176:177], 0, s[18:19]
	global_load_lds_dwordx4 v[254:255], off
.Lgp7_nb:
	s_setprio 1
	v_mfma_f32_16x16x32_bf16 v[124:127], v[128:131], v[144:147], v[124:127]
	v_mfma_f32_16x16x32_bf16 v[120:123], v[132:135], v[144:147], v[120:123]
	v_mfma_f32_16x16x32_bf16 v[116:119], v[136:139], v[144:147], v[116:119]
	v_mfma_f32_16x16x32_bf16 v[112:115], v[140:143], v[144:147], v[112:115]
	v_mfma_f32_16x16x32_bf16 v[108:111], v[128:131], v[148:151], v[108:111]
	v_mfma_f32_16x16x32_bf16 v[104:107], v[132:135], v[148:151], v[104:107]
	v_mfma_f32_16x16x32_bf16 v[100:103], v[136:139], v[148:151], v[100:103]
	v_mfma_f32_16x16x32_bf16 v[96:99], v[140:143], v[148:151], v[96:99]
	v_mfma_f32_16x16x32_bf16 v[92:95], v[128:131], v[152:155], v[92:95]
	v_mfma_f32_16x16x32_bf16 v[88:91], v[132:135], v[152:155], v[88:91]
	v_mfma_f32_16x16x32_bf16 v[84:87], v[136:139], v[152:155], v[84:87]
	v_mfma_f32_16x16x32_bf16 v[80:83], v[140:143], v[152:155], v[80:83]
	v_mfma_f32_16x16x32_bf16 v[76:79], v[128:131], v[156:159], v[76:79]
	v_mfma_f32_16x16x32_bf16 v[72:75], v[132:135], v[156:159], v[72:75]
	v_mfma_f32_16x16x32_bf16 v[68:71], v[136:139], v[156:159], v[68:71]
	v_mfma_f32_16x16x32_bf16 v[64:67], v[140:143], v[156:159], v[64:67]
	v_mfma_f32_16x16x32_bf16 v[60:63], v[128:131], v[160:163], v[60:63]
	v_mfma_f32_16x16x32_bf16 v[56:59], v[132:135], v[160:163], v[56:59]
	v_mfma_f32_16x16x32_bf16 v[52:55], v[136:139], v[160:163], v[52:55]
	v_mfma_f32_16x16x32_bf16 v[48:51], v[140:143], v[160:163], v[48:51]
	v_mfma_f32_16x16x32_bf16 v[44:47], v[128:131], v[164:167], v[44:47]
	v_mfma_f32_16x16x32_bf16 v[40:43], v[132:135], v[164:167], v[40:43]
	v_mfma_f32_16x16x32_bf16 v[36:39], v[136:139], v[164:167], v[36:39]
	v_mfma_f32_16x16x32_bf16 v[32:35], v[140:143], v[164:167], v[32:35]
	v_mfma_f32_16x16x32_bf16 v[28:31], v[128:131], v[196:199], v[28:31]
	v_mfma_f32_16x16x32_bf16 v[24:27], v[132:135], v[196:199], v[24:27]
	v_mfma_f32_16x16x32_bf16 v[20:23], v[136:139], v[196:199], v[20:23]
	v_mfma_f32_16x16x32_bf16 v[16:19], v[140:143], v[196:199], v[16:19]
	v_mfma_f32_16x16x32_bf16 v[12:15], v[128:131], v[200:203], v[12:15]
	v_mfma_f32_16x16x32_bf16 v[8:11], v[132:135], v[200:203], v[8:11]
	v_mfma_f32_16x16x32_bf16 v[4:7], v[136:139], v[200:203], v[4:7]
	v_mfma_f32_16x16x32_bf16 v[0:3], v[140:143], v[200:203], v[0:3]
	s_setprio 0
	s_waitcnt lgkmcnt(0)
	s_and_b64 s[4:5], s[22:23], 0x80
	s_branch .LBB0_1674

; DI f32x4 mfma16(bf16x8 a, bf16x8 b, f32x4 c) { return __builtin_amdgcn_mfma_f32_16x16x32_bf16(a, b, c, 0, 0, 0); }
;     ...
;       for (int m = 0; m < MF; ++m) {
; #pragma unroll
;         for (int n = 0; n < 4; ++n) acc[m][n] = mfma16(bf[n], af[m], acc[m][n]);
.Lgp7_exit:
	s_setprio 1
	v_mfma_f32_16x16x32_bf16 v[124:127], v[204:207], v[220:223], v[124:127]
	v_mfma_f32_16x16x32_bf16 v[120:123], v[208:211], v[220:223], v[120:123]
	v_mfma_f32_16x16x32_bf16 v[116:119], v[212:215], v[220:223], v[116:119]
	v_mfma_f32_16x16x32_bf16 v[112:115], v[216:219], v[220:223], v[112:115]
	v_mfma_f32_16x16x32_bf16 v[108:111], v[204:207], v[224:227], v[108:111]
	v_mfma_f32_16x16x32_bf16 v[104:107], v[208:211], v[224:227], v[104:107]
	v_mfma_f32_16x16x32_bf16 v[100:103], v[212:215], v[224:227], v[100:103]
	v_mfma_f32_16x16x32_bf16 v[96:99], v[216:219], v[224:227], v[96:99]
	v_mfma_f32_16x16x32_bf16 v[92:95], v[204:207], v[228:231], v[92:95]
	v_mfma_f32_16x16x32_bf16 v[88:91], v[208:211], v[228:231], v[88:91]
	v_mfma_f32_16x16x32_bf16 v[84:87], v[212:215], v[228:231], v[84:87]
	v_mfma_f32_16x16x32_bf16 v[80:83], v[216:219], v[228:231], v[80:83]
	v_mfma_f32_16x16x32_bf16 v[76:79], v[204:207], v[232:235], v[76:79]
	v_mfma_f32_16x16x32_bf16 v[72:75], v[208:211], v[232:235], v[72:75]
	v_mfma_f32_16x16x32_bf16 v[68:71], v[212:215], v[232:235], v[68:71]
	v_mfma_f32_16x16x32_bf16 v[64:67], v[216:219], v[232:235], v[64:67]
	v_mfma_f32_16x16x32_bf16 v[60:63], v[204:207], v[238:241], v[60:63]
	v_mfma_f32_16x16x32_bf16 v[56:59], v[208:211], v[238:241], v[56:59]
	v_mfma_f32_16x16x32_bf16 v[52:55], v[212:215], v[238:241], v[52:55]
	v_mfma_f32_16x16x32_bf16 v[48:51], v[216:219], v[238:241], v[48:51]
	v_mfma_f32_16x16x32_bf16 v[44:47], v[204:207], v[242:245], v[44:47]
	v_mfma_f32_16x16x32_bf16 v[40:43], v[208:211], v[242:245], v[40:43]
	v_mfma_f32_16x16x32_bf16 v[36:39], v[212:215], v[242:245], v[36:39]
	v_mfma_f32_16x16x32_bf16 v[32:35], v[216:219], v[242:245], v[32:35]
	v_mfma_f32_16x16x32_bf16 v[28:31], v[204:207], v[246:249], v[28:31]
	v_mfma_f32_16x16x32_bf16 v[24:27], v[208:211], v[246:249], v[24:27]
	v_mfma_f32_16x16x32_bf16 v[20:23], v[212:215], v[246:249], v[20:23]
	v_mfma_f32_16x16x32_bf16 v[16:19], v[216:219], v[246:249], v[16:19]
	v_mfma_f32_16x16x32_bf16 v[12:15], v[204:207], v[250:253], v[12:15]
	v_mfma_f32_16x16x32_bf16 v[8:11], v[208:211], v[250:253], v[8:11]
	v_mfma_f32_16x16x32_bf16 v[4:7], v[212:215], v[250:253], v[4:7]
	v_mfma_f32_16x16x32_bf16 v[0:3], v[216:219], v[250:253], v[0:3]
	s_setprio 0
	s_nop 7
	s_nop 3
	s_branch .LBB0_1691

; DI f32x4 mfma16(bf16x8 a, bf16x8 b, f32x4 c) { return __builtin_amdgcn_mfma_f32_16x16x32_bf16(a, b, c, 0, 0, 0); }
;     ...
; #pragma unroll 1
;   for (int kt = 0; kt < nk; ++kt) {
;     const bool issue = kt + 1 < nk;
;     const int ibuf = buf ^ 1;
; #pragma unroll
;     for (int s2 = 0; s2 < 2; ++s2) {
;       bf16x8 bf[4], af[MF];
;       {
;         const unsigned la = lds_base + buf * 65536 + ((wm * MF) << 11) + (s2 ? lofs1 : lofs0);
;         const unsigned lb = lds_base + buf * 65536 + 32768 + ((wn * 4) << 11) + (s2 ? lofs1 : lofs0);
;         if constexpr (MF == 8) {
;           asm volatile(
;               "ds_read_b128 %0, %13\n\tds_read_b128 %1, %13 offset:2048\n\tds_read_b128 %2, %13 offset:4096\n\tds_read_b128 %3, %13 offset:6144\n\t"
;               "ds_read_b128 %4, %12\n\tds_read_b128 %5, %12 offset:2048\n\tds_read_b128 %6, %12 offset:4096\n\tds_read_b128 %7, %12 offset:6144\n\t"
;               "ds_read_b128 %8, %12 offset:8192\n\tds_read_b128 %9, %12 offset:10240\n\tds_read_b128 %10, %12 offset:12288\n\tds_read_b128 %11, %12 offset:14336\n\t"
;               "s_waitcnt lgkmcnt(0)"
;               : "=&v"(bf[0]), "=&v"(bf[1]), "=&v"(bf[2]), "=&v"(bf[3]), "=&v"(af[0]), "=&v"(af[1]), "=&v"(af[2]), "=&v"(af[3]),
;                 "=&v"(af[4]), "=&v"(af[5]), "=&v"(af[6]), "=&v"(af[7])
;               : "v"(la), "v"(lb)
;               : "memory");
;         } else {
;           asm volatile(
;               "ds_read_b128 %0, %9\n\tds_read_b128 %1, %9 offset:2048\n\tds_read_b128 %2, %9 offset:4096\n\tds_read_b128 %3, %9 offset:6144\n\t"
;               "ds_read_b128 %4, %8\n\tds_read_b128 %5, %8 offset:2048\n\tds_read_b128 %6, %8 offset:4096\n\tds_read_b128 %7, %8 offset:6144\n\t"
;               "s_waitcnt lgkmcnt(0)"
;               : "=&v"(bf[0]), "=&v"(bf[1]), "=&v"(bf[2]), "=&v"(bf[3]), "=&v"(af[0]), "=&v"(af[1]), "=&v"(af[2]), "=&v"(af[3])
;               : "v"(la), "v"(lb)
;               : "memory");
;         }
;       }
;       __builtin_amdgcn_sched_barrier(0);
;       __builtin_amdgcn_s_setprio(1);
; #pragma unroll
;       for (int m = 0; m < MF; ++m) {
; #pragma unroll
;         for (int n = 0; n < 4; ++n) acc[m][n] = mfma16(bf[n], af[m], acc[m][n]);
;         if constexpr (MF == 8) {
;           if (m & 1) {
;             __builtin_amdgcn_sched_barrier(0);
;             if (issue) {
.LBB0_1724:
	s_mov_b32 s4, s29
	s_cmp_lt_u32 s28, 15
	s_cselect_b64 s[22:23], -1, 0
	s_lshl_b32 s4, s4, 16
	v_add3_u32 v234, s4, v178, v180
	v_add3_u32 v235, s4, v179, v180
	ds_read_b128 v[128:131], v235
	ds_read_b128 v[132:135], v235 offset:2048
	ds_read_b128 v[136:139], v235 offset:4096
	ds_read_b128 v[140:143], v235 offset:6144
	ds_read_b128 v[144:147], v234
	ds_read_b128 v[148:151], v234 offset:2048
	ds_read_b128 v[152:155], v234 offset:4096
	ds_read_b128 v[156:159], v234 offset:6144
	ds_read_b128 v[160:163], v234 offset:8192
	ds_read_b128 v[164:167], v234 offset:10240
	ds_read_b128 v[194:197], v234 offset:12288
	ds_read_b128 v[198:201], v234 offset:14336
	v_add3_u32 v234, s4, v178, v181
	v_add3_u32 v235, s4, v179, v181
	s_xor_b32 s29, s29, 1
	s_lshl_b32 s5, s29, 16
	v_readfirstlane_b32 s98, v177
	s_add_u32 s98, s98, s5
	s_cmp_eq_u64 s[22:23], 0
	s_cbranch_scc1 .Lgp8_na
	s_mov_b32 m0, s98
	s_nop 0
	global_load_lds_dwordx4 v[172:173], off
	s_add_u32 m0, s98, 0x400
	v_lshl_add_u64 v[254:255], v[172:173], 0, s[14:15]
	global_load_lds_dwordx4 v[254:255], off
	s_add_u32 m0, s98, 0x800
	v_lshl_add_u64 v[254:255], v[172:173], 0, s[16:17]
	global_load_lds_dwordx4 v[254:255], off
	s_add_u32 m0, s98, 0xc00
	v_lshl_add_u64 v[254:255], v[172:173], 0, s[18:19]
	global_load_lds_dwordx4 v[254:255], off

;     ...
;   for (int kt = 0; kt < nk; ++kt) {
;     const bool issue = kt + 1 < nk;
;     const int ibuf = buf ^ 1;
; #pragma unroll
;     for (int s2 = 0; s2 < 2; ++s2) {
;       bf16x8 bf[4], af[MF];
;       {
;         const unsigned la = lds_base + buf * 65536 + ((wm * MF) << 11) + (s2 ? lofs1 : lofs0);
;         const unsigned lb = lds_base + buf * 65536 + 32768 + ((wn * 4) << 11) + (s2 ? lofs1 : lofs0);
;         if constexpr (MF == 8) {
;           asm volatile(
;               "ds_read_b128 %0, %13\n\tds_read_b128 %1, %13 offset:2048\n\tds_read_b128 %2, %13 offset:4096\n\tds_read_b128 %3, %13 offset:6144\n\t"
;               "ds_read_b128 %4, %12\n\tds_read_b128 %5, %12 offset:2048\n\tds_read_b128 %6, %12 offset:4096\n\tds_read_b128 %7, %12 offset:6144\n\t"
;               "ds_read_b128 %8, %12 offset:8192\n\tds_read_b128 %9, %12 offset:10240\n\tds_read_b128 %10, %12 offset:12288\n\tds_read_b128 %11, %12 offset:14336\n\t"
;               "s_waitcnt lgkmcnt(0)"
;               : "=&v"(bf[0]), "=&v"(bf[1]), "=&v"(bf[2]), "=&v"(bf[3]), "=&v"(af[0]), "=&v"(af[1]), "=&v"(af[2]), "=&v"(af[3]),
;                 "=&v"(af[4]), "=&v"(af[5]), "=&v"(af[6]), "=&v"(af[7])
;               : "v"(la), "v"(lb)
;               : "memory");
;         } else {
;           asm volatile(
;               "ds_read_b128 %0, %9\n\tds_read_b128 %1, %9 offset:2048\n\tds_read_b128 %2, %9 offset:4096\n\tds_read_b128 %3, %9 offset:6144\n\t"
;               "ds_read_b128 %4, %8\n\tds_read_b128 %5, %8 offset:2048\n\tds_read_b128 %6, %8 offset:4096\n\tds_read_b128 %7, %8 offset:6144\n\t"
;               "s_waitcnt lgkmcnt(0)"
;               : "=&v"(bf[0]), "=&v"(bf[1]), "=&v"(bf[2]), "=&v"(bf[3]), "=&v"(af[0]), "=&v"(af[1]), "=&v"(af[2]), "=&v"(af[3])
;               : "v"(la), "v"(lb)
;               : "memory");
;         }
;       }
;       __builtin_amdgcn_sched_barrier(0);
;       __builtin_amdgcn_s_setprio(1);
; #pragma unroll
;       for (int m = 0; m < MF; ++m) {
; #pragma unroll
;         for (int n = 0; n < 4; ++n) acc[m][n] = mfma16(bf[n], af[m], acc[m][n]);
;         if constexpr (MF == 8) {
;           if (m & 1) {
;             __builtin_amdgcn_sched_barrier(0);
;             if (issue) {
;               if (s2 == 0) { if (m == 1) GEMM_PIECE_A(ibuf, 0); if (m == 3) GEMM_PIECE_A(ibuf, 1); if (m == 5) GEMM_PIECE_A(ibuf, 2); if (m == 7) GEMM_PIECE_A(ibuf, 3); }
.Lgp8_mid:
	s_waitcnt lgkmcnt(0)
	ds_read_b128 v[202:205], v235
	ds_read_b128 v[206:209], v235 offset:2048
	ds_read_b128 v[210:213], v235 offset:4096
	ds_read_b128 v[214:217], v235 offset:6144
	ds_read_b128 v[218:221], v234
	ds_read_b128 v[222:225], v234 offset:2048
	ds_read_b128 v[226:229], v234 offset:4096
	ds_read_b128 v[230:233], v234 offset:6144
	ds_read_b128 v[238:241], v234 offset:8192
	ds_read_b128 v[242:245], v234 offset:10240
	ds_read_b128 v[246:249], v234 offset:12288
	ds_read_b128 v[250:253], v234 offset:14336
	s_cmp_eq_u64 s[22:23], 0
	s_cbranch_scc1 .Lgp8_nb
	s_add_u32 m0, s98, 0x8000
	s_nop 0
	global_load_lds_dwordx4 v[174:175], off
	s_add_u32 m0, s98, 0x8400
	v_lshl_add_u64 v[254:255], v[174:175], 0, s[14:15]
	global_load_lds_dwordx4 v[254:255], off
	s_add_u32 m0, s98, 0x8800
	v_lshl_add_u64 v[254:255], v[174:175], 0, s[16:17]
	global_load_lds_dwordx4 v[254:255], off
	s_add_u32 m0, s98, 0x8c00
	v_lshl_add_u64 v[254:255], v[174:175], 0, s[18:19]
	global_load_lds_dwordx4 v[254:255], off
.Lgp8_nb:
	s_setprio 1
	v_mfma_f32_16x16x32_bf16 v[124:127], v[128:131], v[144:147], v[124:127]
	v_mfma_f32_16x16x32_bf16 v[120:123], v[132:135], v[144:147], v[120:123]
	v_mfma_f32_16x16x32_bf16 v[116:119], v[136:139], v[144:147], v[116:119]
	v_mfma_f32_16x16x32_bf16 v[112:115], v[140:143], v[144:147], v[112:115]
	v_mfma_f32_16x16x32_bf16 v[108:111], v[128:131], v[148:151], v[108:111]
	v_mfma_f32_16x16x32_bf16 v[104:107], v[132:135], v[148:151], v[104:107]
	v_mfma_f32_16x16x32_bf16 v[100:103], v[136:139], v[148:151], v[100:103]
	v_mfma_f32_16x16x32_bf16 v[96:99], v[140:143], v[148:151], v[96:99]
	v_mfma_f32_16x16x32_bf16 v[92:95], v[128:131], v[152:155], v[92:95]
	v_mfma_f32_16x16x32_bf16 v[88:91], v[132:135], v[152:155], v[88:91]
	v_mfma_f32_16x16x32_bf16 v[84:87], v[136:139], v[152:155], v[84:87]
	v_mfma_f32_16x16x32_bf16 v[80:83], v[140:143], v[152:155], v[80:83]
	v_mfma_f32_16x16x32_bf16 v[76:79], v[128:131], v[156:159], v[76:79]
	v_mfma_f32_16x16x32_bf16 v[72:75], v[132:135], v[156:159], v[72:75]
	v_mfma_f32_16x16x32_bf16 v[68:71], v[136:139], v[156:159], v[68:71]
	v_mfma_f32_16x16x32_bf16 v[64:67], v[140:143], v[156:159], v[64:67]
	v_mfma_f32_16x16x32_bf16 v[60:63], v[128:131], v[160:163], v[60:63]
	v_mfma_f32_16x16x32_bf16 v[56:59], v[132:135], v[160:163], v[56:59]
	v_mfma_f32_16x16x32_bf16 v[52:55], v[136:139], v[160:163], v[52:55]
	v_mfma_f32_16x16x32_bf16 v[48:51], v[140:143], v[160:163], v[48:51]
	v_mfma_f32_16x16x32_bf16 v[44:47], v[128:131], v[164:167], v[44:47]
	v_mfma_f32_16x16x32_bf16 v[40:43], v[132:135], v[164:167], v[40:43]
	v_mfma_f32_16x16x32_bf16 v[36:39], v[136:139], v[164:167], v[36:39]
	v_mfma_f32_16x16x32_bf16 v[32:35], v[140:143], v[164:167], v[32:35]
	v_mfma_f32_16x16x32_bf16 v[28:31], v[128:131], v[194:197], v[28:31]
	v_mfma_f32_16x16x32_bf16 v[24:27], v[132:135], v[194:197], v[24:27]
	v_mfma_f32_16x16x32_bf16 v[20:23], v[136:139], v[194:197], v[20:23]
	v_mfma_f32_16x16x32_bf16 v[16:19], v[140:143], v[194:197], v[16:19]
	v_mfma_f32_16x16x32_bf16 v[12:15], v[128:131], v[198:201], v[12:15]
	v_mfma_f32_16x16x32_bf16 v[8:11], v[132:135], v[198:201], v[8:11]
	v_mfma_f32_16x16x32_bf16 v[4:7], v[136:139], v[198:201], v[4:7]
	v_mfma_f32_16x16x32_bf16 v[0:3], v[140:143], v[198:201], v[0:3]
	s_setprio 0
	s_waitcnt lgkmcnt(0)
	s_and_b64 s[4:5], s[22:23], 0x80
	s_branch .LBB0_1723

; DI f32x4 mfma16(bf16x8 a, bf16x8 b, f32x4 c) { return __builtin_amdgcn_mfma_f32_16x16x32_bf16(a, b, c, 0, 0, 0); }
;     ...
; #pragma unroll 1
;   for (int kt = 0; kt < nk; ++kt) {
;     const bool issue = kt + 1 < nk;
;     const int ibuf = buf ^ 1;
; #pragma unroll
;     for (int s2 = 0; s2 < 2; ++s2) {
;       bf16x8 bf[4], af[MF];
;       {
;         const unsigned la = lds_base + buf * 65536 + ((wm * MF) << 11) + (s2 ? lofs1 : lofs0);
;         const unsigned lb = lds_base + buf * 65536 + 32768 + ((wn * 4) << 11) + (s2 ? lofs1 : lofs0);
;         if constexpr (MF == 8) {
;           asm volatile(
;               "ds_read_b128 %0, %13\n\tds_read_b128 %1, %13 offset:2048\n\tds_read_b128 %2, %13 offset:4096\n\tds_read_b128 %3, %13 offset:6144\n\t"
;               "ds_read_b128 %4, %12\n\tds_read_b128 %5, %12 offset:2048\n\tds_read_b128 %6, %12 offset:4096\n\tds_read_b128 %7, %12 offset:6144\n\t"
;               "ds_read_b128 %8, %12 offset:8192\n\tds_read_b128 %9, %12 offset:10240\n\tds_read_b128 %10, %12 offset:12288\n\tds_read_b128 %11, %12 offset:14336\n\t"
;               "s_waitcnt lgkmcnt(0)"
;               : "=&v"(bf[0]), "=&v"(bf[1]), "=&v"(bf[2]), "=&v"(bf[3]), "=&v"(af[0]), "=&v"(af[1]), "=&v"(af[2]), "=&v"(af[3]),
;                 "=&v"(af[4]), "=&v"(af[5]), "=&v"(af[6]), "=&v"(af[7])
;               : "v"(la), "v"(lb)
;               : "memory");
;         } else {
;           asm volatile(
;               "ds_read_b128 %0, %9\n\tds_read_b128 %1, %9 offset:2048\n\tds_read_b128 %2, %9 offset:4096\n\tds_read_b128 %3, %9 offset:6144\n\t"
;               "ds_read_b128 %4, %8\n\tds_read_b128 %5, %8 offset:2048\n\tds_read_b128 %6, %8 offset:4096\n\tds_read_b128 %7, %8 offset:6144\n\t"
;               "s_waitcnt lgkmcnt(0)"
;               : "=&v"(bf[0]), "=&v"(bf[1]), "=&v"(bf[2]), "=&v"(bf[3]), "=&v"(af[0]), "=&v"(af[1]), "=&v"(af[2]), "=&v"(af[3])
;               : "v"(la), "v"(lb)
;               : "memory");
;         }
;       }
;       __builtin_amdgcn_sched_barrier(0);
;       __builtin_amdgcn_s_setprio(1);
; #pragma unroll
;       for (int m = 0; m < MF; ++m) {
; #pragma unroll
;         for (int n = 0; n < 4; ++n) acc[m][n] = mfma16(bf[n], af[m], acc[m][n]);
;         if constexpr (MF == 8) {
;           if (m & 1) {
;             __builtin_amdgcn_sched_barrier(0);
;             if (issue) {
.LBB0_1902:
	s_mov_b32 s2, s6
	s_cmp_lg_u32 s5, 1
	s_cselect_b64 s[0:1], -1, 0
	s_lshl_b32 s2, s2, 16
	v_add3_u32 v195, s2, v178, v180
	v_add3_u32 v236, s2, v179, v180
	ds_read_b128 v[128:131], v236
	ds_read_b128 v[132:135], v236 offset:2048
	ds_read_b128 v[136:139], v236 offset:4096
	ds_read_b128 v[140:143], v236 offset:6144
	ds_read_b128 v[144:147], v195
	ds_read_b128 v[148:151], v195 offset:2048
	ds_read_b128 v[152:155], v195 offset:4096
	ds_read_b128 v[156:159], v195 offset:6144
	ds_read_b128 v[160:163], v195 offset:8192
	ds_read_b128 v[164:167], v195 offset:10240
	ds_read_b128 v[196:199], v195 offset:12288
	ds_read_b128 v[200:203], v195 offset:14336
	v_add3_u32 v195, s2, v178, v181
	v_add3_u32 v236, s2, v179, v181
	s_xor_b32 s6, s6, 1
	s_lshl_b32 s3, s6, 16
	v_readfirstlane_b32 s98, v177
	s_add_u32 s98, s98, s3
	s_cmp_eq_u64 s[0:1], 0
	s_cbranch_scc1 .Lgp9_na
	s_mov_b32 m0, s98
	s_nop 0
	global_load_lds_dwordx4 v[172:173], off
	s_add_u32 m0, s98, 0x400
	v_lshl_add_u64 v[254:255], v[172:173], 0, s[24:25]
	global_load_lds_dwordx4 v[254:255], off
	s_add_u32 m0, s98, 0x800
	v_lshl_add_u64 v[254:255], v[172:173], 0, s[26:27]
	global_load_lds_dwordx4 v[254:255], off
	s_add_u32 m0, s98, 0xc00
	v_lshl_add_u64 v[254:255], v[172:173], 0, s[28:29]
	global_load_lds_dwordx4 v[254:255], off
.Lgp9_na:
	s_setprio 1
	v_mfma_f32_16x16x32_bf16 v[124:127], v[204:207], v[220:223], v[124:127]
	v_mfma_f32_16x16x32_bf16 v[120:123], v[208:211], v[220:223], v[120:123]
	v_mfma_f32_16x16x32_bf16 v[116:119], v[212:215], v[220:223], v[116:119]
	v_mfma_f32_16x16x32_bf16 v[112:115], v[216:219], v[220:223], v[112:115]
	v_mfma_f32_16x16x32_bf16 v[108:111], v[204:207], v[224:227], v[108:111]
	v_mfma_f32_16x16x32_bf16 v[104:107], v[208:211], v[224:227], v[104:107]
	v_mfma_f32_16x16x32_bf16 v[100:103], v[212:215], v[224:227], v[100:103]
	v_mfma_f32_16x16x32_bf16 v[96:99], v[216:219], v[224:227], v[96:99]
	v_mfma_f32_16x16x32_bf16 v[92:95], v[204:207], v[228:231], v[92:95]
	v_mfma_f32_16x16x32_bf16 v[88:91], v[208:211], v[228:231], v[88:91]
	v_mfma_f32_16x16x32_bf16 v[84:87], v[212:215], v[228:231], v[84:87]
	v_mfma_f32_16x16x32_bf16 v[80:83], v[216:219], v[228:231], v[80:83]
	v_mfma_f32_16x16x32_bf16 v[76:79], v[204:207], v[232:235], v[76:79]
	v_mfma_f32_16x16x32_bf16 v[72:75], v[208:211], v[232:235], v[72:75]
	v_mfma_f32_16x16x32_bf16 v[68:71], v[212:215], v[232:235], v[68:71]
	v_mfma_f32_16x16x32_bf16 v[64:67], v[216:219], v[232:235], v[64:67]
	v_mfma_f32_16x16x32_bf16 v[60:63], v[204:207], v[238:241], v[60:63]
	v_mfma_f32_16x16x32_bf16 v[56:59], v[208:211], v[238:241], v[56:59]
	v_mfma_f32_16x16x32_bf16 v[52:55], v[212:215], v[238:241], v[52:55]
	v_mfma_f32_16x16x32_bf16 v[48:51], v[216:219], v[238:241], v[48:51]
	v_mfma_f32_16x16x32_bf16 v[44:47], v[204:207], v[242:245], v[44:47]
	v_mfma_f32_16x16x32_bf16 v[40:43], v[208:211], v[242:245], v[40:43]
	v_mfma_f32_16x16x32_bf16 v[32:35], v[212:215], v[242:245], v[32:35]
	v_mfma_f32_16x16x32_bf16 v[20:23], v[216:219], v[242:245], v[20:23]
	v_mfma_f32_16x16x32_bf16 v[36:39], v[204:207], v[246:249], v[36:39]
	v_mfma_f32_16x16x32_bf16 v[28:31], v[208:211], v[246:249], v[28:31]
	v_mfma_f32_16x16x32_bf16 v[24:27], v[212:215], v[246:249], v[24:27]
	v_mfma_f32_16x16x32_bf16 v[16:19], v[216:219], v[246:249], v[16:19]
	v_mfma_f32_16x16x32_bf16 v[12:15], v[204:207], v[250:253], v[12:15]
	v_mfma_f32_16x16x32_bf16 v[8:11], v[208:211], v[250:253], v[8:11]
	v_mfma_f32_16x16x32_bf16 v[4:7], v[212:215], v[250:253], v[4:7]
	v_mfma_f32_16x16x32_bf16 v[0:3], v[216:219], v[250:253], v[0:3]
	s_setprio 0
.Lgp9_mid:
	s_waitcnt lgkmcnt(0)
	ds_read_b128 v[204:207], v236
	ds_read_b128 v[208:211], v236 offset:2048
	ds_read_b128 v[212:215], v236 offset:4096
	ds_read_b128 v[216:219], v236 offset:6144
	ds_read_b128 v[220:223], v195
	ds_read_b128 v[224:227], v195 offset:2048
	ds_read_b128 v[228:231], v195 offset:4096
	ds_read_b128 v[232:235], v195 offset:6144
	ds_read_b128 v[238:241], v195 offset:8192
	ds_read_b128 v[242:245], v195 offset:10240
	ds_read_b128 v[246:249], v195 offset:12288
	ds_read_b128 v[250:253], v195 offset:14336
	s_cmp_eq_u64 s[0:1], 0
	s_cbranch_scc1 .Lgp9_nb
	s_add_u32 m0, s98, 0x8000
	s_nop 0
	global_load_lds_dwordx4 v[174:175], off
	s_add_u32 m0, s98, 0x8400
	v_lshl_add_u64 v[254:255], v[174:175], 0, s[24:25]
	global_load_lds_dwordx4 v[254:255], off
	s_add_u32 m0, s98, 0x8800
	v_lshl_add_u64 v[254:255], v[174:175], 0, s[26:27]
	global_load_lds_dwordx4 v[254:255], off
	s_add_u32 m0, s98, 0x8c00
	v_lshl_add_u64 v[254:255], v[174:175], 0, s[28:29]
	global_load_lds_dwordx4 v[254:255], off
.Lgp9_nb:
	s_setprio 1
	v_mfma_f32_16x16x32_bf16 v[124:127], v[128:131], v[144:147], v[124:127]
	v_mfma_f32_16x16x32_bf16 v[120:123], v[132:135], v[144:147], v[120:123]
	v_mfma_f32_16x16x32_bf16 v[116:119], v[136:139], v[144:147], v[116:119]
	v_mfma_f32_16x16x32_bf16 v[112:115], v[140:143], v[144:147], v[112:115]
	v_mfma_f32_16x16x32_bf16 v[108:111], v[128:131], v[148:151], v[108:111]
	v_mfma_f32_16x16x32_bf16 v[104:107], v[132:135], v[148:151], v[104:107]
	v_mfma_f32_16x16x32_bf16 v[100:103], v[136:139], v[148:151], v[100:103]
	v_mfma_f32_16x16x32_bf16 v[96:99], v[140:143], v[148:151], v[96:99]
	v_mfma_f32_16x16x32_bf16 v[92:95], v[128:131], v[152:155], v[92:95]
	v_mfma_f32_16x16x32_bf16 v[88:91], v[132:135], v[152:155], v[88:91]
	v_mfma_f32_16x16x32_bf16 v[84:87], v[136:139], v[152:155], v[84:87]
	v_mfma_f32_16x16x32_bf16 v[80:83], v[140:143], v[152:155], v[80:83]
	v_mfma_f32_16x16x32_bf16 v[76:79], v[128:131], v[156:159], v[76:79]
	v_mfma_f32_16x16x32_bf16 v[72:75], v[132:135], v[156:159], v[72:75]
	v_mfma_f32_16x16x32_bf16 v[68:71], v[136:139], v[156:159], v[68:71]
	v_mfma_f32_16x16x32_bf16 v[64:67], v[140:143], v[156:159], v[64:67]
	v_mfma_f32_16x16x32_bf16 v[60:63], v[128:131], v[160:163], v[60:63]
	v_mfma_f32_16x16x32_bf16 v[56:59], v[132:135], v[160:163], v[56:59]
	v_mfma_f32_16x16x32_bf16 v[52:55], v[136:139], v[160:163], v[52:55]
	v_mfma_f32_16x16x32_bf16 v[48:51], v[140:143], v[160:163], v[48:51]
	v_mfma_f32_16x16x32_bf16 v[44:47], v[128:131], v[164:167], v[44:47]
	v_mfma_f32_16x16x32_bf16 v[40:43], v[132:135], v[164:167], v[40:43]
	v_mfma_f32_16x16x32_bf16 v[32:35], v[136:139], v[164:167], v[32:35]
	v_mfma_f32_16x16x32_bf16 v[20:23], v[140:143], v[164:167], v[20:23]
	v_mfma_f32_16x16x32_bf16 v[36:39], v[128:131], v[196:199], v[36:39]
	v_mfma_f32_16x16x32_bf16 v[28:31], v[132:135], v[196:199], v[28:31]
	v_mfma_f32_16x16x32_bf16 v[24:27], v[136:139], v[196:199], v[24:27]
	v_mfma_f32_16x16x32_bf16 v[16:19], v[140:143], v[196:199], v[16:19]
	v_mfma_f32_16x16x32_bf16 v[12:15], v[128:131], v[200:203], v[12:15]
	v_mfma_f32_16x16x32_bf16 v[8:11], v[132:135], v[200:203], v[8:11]
	v_mfma_f32_16x16x32_bf16 v[4:7], v[136:139], v[200:203], v[4:7]
	v_mfma_f32_16x16x32_bf16 v[0:3], v[140:143], v[200:203], v[0:3]
	s_setprio 0
	s_waitcnt lgkmcnt(0)
	s_and_b64 s[0:1], s[0:1], 0x80
	s_branch .LBB0_1901

; DI f32x4 mfma16(bf16x8 a, bf16x8 b, f32x4 c) { return __builtin_amdgcn_mfma_f32_16x16x32_bf16(a, b, c, 0, 0, 0); }
;     ...
;       for (int m = 0; m < MF; ++m) {
; #pragma unroll
;         for (int n = 0; n < 4; ++n) acc[m][n] = mfma16(bf[n], af[m], acc[m][n]);
.Lgp9_exit:
	s_setprio 1
	v_mfma_f32_16x16x32_bf16 v[124:127], v[204:207], v[220:223], v[124:127]
	v_mfma_f32_16x16x32_bf16 v[120:123], v[208:211], v[220:223], v[120:123]
	v_mfma_f32_16x16x32_bf16 v[116:119], v[212:215], v[220:223], v[116:119]
	v_mfma_f32_16x16x32_bf16 v[112:115], v[216:219], v[220:223], v[112:115]
	v_mfma_f32_16x16x32_bf16 v[108:111], v[204:207], v[224:227], v[108:111]
	v_mfma_f32_16x16x32_bf16 v[104:107], v[208:211], v[224:227], v[104:107]
	v_mfma_f32_16x16x32_bf16 v[100:103], v[212:215], v[224:227], v[100:103]
	v_mfma_f32_16x16x32_bf16 v[96:99], v[216:219], v[224:227], v[96:99]
	v_mfma_f32_16x16x32_bf16 v[92:95], v[204:207], v[228:231], v[92:95]
	v_mfma_f32_16x16x32_bf16 v[88:91], v[208:211], v[228:231], v[88:91]
	v_mfma_f32_16x16x32_bf16 v[84:87], v[212:215], v[228:231], v[84:87]
	v_mfma_f32_16x16x32_bf16 v[80:83], v[216:219], v[228:231], v[80:83]
	v_mfma_f32_16x16x32_bf16 v[76:79], v[204:207], v[232:235], v[76:79]
	v_mfma_f32_16x16x32_bf16 v[72:75], v[208:211], v[232:235], v[72:75]
	v_mfma_f32_16x16x32_bf16 v[68:71], v[212:215], v[232:235], v[68:71]
	v_mfma_f32_16x16x32_bf16 v[64:67], v[216:219], v[232:235], v[64:67]
	v_mfma_f32_16x16x32_bf16 v[60:63], v[204:207], v[238:241], v[60:63]
	v_mfma_f32_16x16x32_bf16 v[56:59], v[208:211], v[238:241], v[56:59]
	v_mfma_f32_16x16x32_bf16 v[52:55], v[212:215], v[238:241], v[52:55]
	v_mfma_f32_16x16x32_bf16 v[48:51], v[216:219], v[238:241], v[48:51]
	v_mfma_f32_16x16x32_bf16 v[44:47], v[204:207], v[242:245], v[44:47]
	v_mfma_f32_16x16x32_bf16 v[40:43], v[208:211], v[242:245], v[40:43]
	v_mfma_f32_16x16x32_bf16 v[32:35], v[212:215], v[242:245], v[32:35]
	v_mfma_f32_16x16x32_bf16 v[20:23], v[216:219], v[242:245], v[20:23]
	v_mfma_f32_16x16x32_bf16 v[36:39], v[204:207], v[246:249], v[36:39]
	v_mfma_f32_16x16x32_bf16 v[28:31], v[208:211], v[246:249], v[28:31]
	v_mfma_f32_16x16x32_bf16 v[24:27], v[212:215], v[246:249], v[24:27]
	v_mfma_f32_16x16x32_bf16 v[16:19], v[216:219], v[246:249], v[16:19]
	v_mfma_f32_16x16x32_bf16 v[12:15], v[204:207], v[250:253], v[12:15]
	v_mfma_f32_16x16x32_bf16 v[8:11], v[208:211], v[250:253], v[8:11]
	v_mfma_f32_16x16x32_bf16 v[4:7], v[212:215], v[250:253], v[4:7]
	v_mfma_f32_16x16x32_bf16 v[0:3], v[216:219], v[250:253], v[0:3]
	s_setprio 0
	s_nop 7
	s_nop 3
	s_branch .LBB0_1918

; DI f32x4 mfma16(bf16x8 a, bf16x8 b, f32x4 c) { return __builtin_amdgcn_mfma_f32_16x16x32_bf16(a, b, c, 0, 0, 0); }
;     ...
; #pragma unroll 1
;   for (int kt = 0; kt < nk; ++kt) {
;     const bool issue = kt + 1 < nk;
;     const int ibuf = buf ^ 1;
; #pragma unroll
;     for (int s2 = 0; s2 < 2; ++s2) {
;       bf16x8 bf[4], af[MF];
;       {
;         const unsigned la = lds_base + buf * 65536 + ((wm * MF) << 11) + (s2 ? lofs1 : lofs0);
;         const unsigned lb = lds_base + buf * 65536 + 32768 + ((wn * 4) << 11) + (s2 ? lofs1 : lofs0);
;         if constexpr (MF == 8) {
;           asm volatile(
;               "ds_read_b128 %0, %13\n\tds_read_b128 %1, %13 offset:2048\n\tds_read_b128 %2, %13 offset:4096\n\tds_read_b128 %3, %13 offset:6144\n\t"
;               "ds_read_b128 %4, %12\n\tds_read_b128 %5, %12 offset:2048\n\tds_read_b128 %6, %12 offset:4096\n\tds_read_b128 %7, %12 offset:6144\n\t"
;               "ds_read_b128 %8, %12 offset:8192\n\tds_read_b128 %9, %12 offset:10240\n\tds_read_b128 %10, %12 offset:12288\n\tds_read_b128 %11, %12 offset:14336\n\t"
;               "s_waitcnt lgkmcnt(0)"
;               : "=&v"(bf[0]), "=&v"(bf[1]), "=&v"(bf[2]), "=&v"(bf[3]), "=&v"(af[0]), "=&v"(af[1]), "=&v"(af[2]), "=&v"(af[3]),
;                 "=&v"(af[4]), "=&v"(af[5]), "=&v"(af[6]), "=&v"(af[7])
;               : "v"(la), "v"(lb)
;               : "memory");
;         } else {
;           asm volatile(
;               "ds_read_b128 %0, %9\n\tds_read_b128 %1, %9 offset:2048\n\tds_read_b128 %2, %9 offset:4096\n\tds_read_b128 %3, %9 offset:6144\n\t"
;               "ds_read_b128 %4, %8\n\tds_read_b128 %5, %8 offset:2048\n\tds_read_b128 %6, %8 offset:4096\n\tds_read_b128 %7, %8 offset:6144\n\t"
;               "s_waitcnt lgkmcnt(0)"
;               : "=&v"(bf[0]), "=&v"(bf[1]), "=&v"(bf[2]), "=&v"(bf[3]), "=&v"(af[0]), "=&v"(af[1]), "=&v"(af[2]), "=&v"(af[3])
;               : "v"(la), "v"(lb)
;               : "memory");
;         }
;       }
;       __builtin_amdgcn_sched_barrier(0);
;       __builtin_amdgcn_s_setprio(1);
; #pragma unroll
;       for (int m = 0; m < MF; ++m) {
; #pragma unroll
;         for (int n = 0; n < 4; ++n) acc[m][n] = mfma16(bf[n], af[m], acc[m][n]);
;         if constexpr (MF == 8) {
;           if (m & 1) {
;             __builtin_amdgcn_sched_barrier(0);
;             if (issue) {
.LBB0_2083:
	s_mov_b32 s4, s30
	s_cmp_lt_u32 s29, 43
	s_cselect_b64 s[22:23], -1, 0
	s_lshl_b32 s4, s4, 16
	v_add3_u32 v195, s4, v168, v181
	v_add3_u32 v236, s4, v180, v181
	ds_read_b128 v[128:131], v236
	ds_read_b128 v[132:135], v236 offset:2048
	ds_read_b128 v[136:139], v236 offset:4096
	ds_read_b128 v[140:143], v236 offset:6144
	ds_read_b128 v[144:147], v195
	ds_read_b128 v[148:151], v195 offset:2048
	ds_read_b128 v[152:155], v195 offset:4096
	ds_read_b128 v[156:159], v195 offset:6144
	ds_read_b128 v[160:163], v195 offset:8192
	ds_read_b128 v[164:167], v195 offset:10240
	ds_read_b128 v[196:199], v195 offset:12288
	ds_read_b128 v[200:203], v195 offset:14336
	v_add3_u32 v195, s4, v168, v182
	v_add3_u32 v236, s4, v180, v182
	s_xor_b32 s30, s30, 1
	s_lshl_b32 s5, s30, 16
	v_readfirstlane_b32 s98, v179
	s_add_u32 s98, s98, s5
	s_cmp_eq_u64 s[22:23], 0
	s_cbranch_scc1 .Lgp11_na
	s_mov_b32 m0, s98
	s_nop 0
	global_load_lds_dwordx4 v[174:175], off
	s_add_u32 m0, s98, 0x400
	v_lshl_add_u64 v[254:255], v[174:175], 0, s[14:15]
	global_load_lds_dwordx4 v[254:255], off
	s_add_u32 m0, s98, 0x800
	v_lshl_add_u64 v[254:255], v[174:175], 0, s[16:17]
	global_load_lds_dwordx4 v[254:255], off
	s_add_u32 m0, s98, 0xc00
	v_lshl_add_u64 v[254:255], v[174:175], 0, s[18:19]
	global_load_lds_dwordx4 v[254:255], off

; DI f32x4 mfma16(bf16x8 a, bf16x8 b, f32x4 c) { return __builtin_amdgcn_mfma_f32_16x16x32_bf16(a, b, c, 0, 0, 0); }
;     ...
; #pragma unroll 1
;   for (int kt = 0; kt < nk; ++kt) {
;     const bool issue = kt + 1 < nk;
;     const int ibuf = buf ^ 1;
; #pragma unroll
;     for (int s2 = 0; s2 < 2; ++s2) {
;       bf16x8 bf[4], af[MF];
;       {
;         const unsigned la = lds_base + buf * 65536 + ((wm * MF) << 11) + (s2 ? lofs1 : lofs0);
;         const unsigned lb = lds_base + buf * 65536 + 32768 + ((wn * 4) << 11) + (s2 ? lofs1 : lofs0);
;         if constexpr (MF == 8) {
;           asm volatile(
;               "ds_read_b128 %0, %13\n\tds_read_b128 %1, %13 offset:2048\n\tds_read_b128 %2, %13 offset:4096\n\tds_read_b128 %3, %13 offset:6144\n\t"
;               "ds_read_b128 %4, %12\n\tds_read_b128 %5, %12 offset:2048\n\tds_read_b128 %6, %12 offset:4096\n\tds_read_b128 %7, %12 offset:6144\n\t"
;               "ds_read_b128 %8, %12 offset:8192\n\tds_read_b128 %9, %12 offset:10240\n\tds_read_b128 %10, %12 offset:12288\n\tds_read_b128 %11, %12 offset:14336\n\t"
;               "s_waitcnt lgkmcnt(0)"
;               : "=&v"(bf[0]), "=&v"(bf[1]), "=&v"(bf[2]), "=&v"(bf[3]), "=&v"(af[0]), "=&v"(af[1]), "=&v"(af[2]), "=&v"(af[3]),
;                 "=&v"(af[4]), "=&v"(af[5]), "=&v"(af[6]), "=&v"(af[7])
;               : "v"(la), "v"(lb)
;               : "memory");
;         } else {
;           asm volatile(
;               "ds_read_b128 %0, %9\n\tds_read_b128 %1, %9 offset:2048\n\tds_read_b128 %2, %9 offset:4096\n\tds_read_b128 %3, %9 offset:6144\n\t"
;               "ds_read_b128 %4, %8\n\tds_read_b128 %5, %8 offset:2048\n\tds_read_b128 %6, %8 offset:4096\n\tds_read_b128 %7, %8 offset:6144\n\t"
;               "s_waitcnt lgkmcnt(0)"
;               : "=&v"(bf[0]), "=&v"(bf[1]), "=&v"(bf[2]), "=&v"(bf[3]), "=&v"(af[0]), "=&v"(af[1]), "=&v"(af[2]), "=&v"(af[3])
;               : "v"(la), "v"(lb)
;               : "memory");
;         }
;       }
;       __builtin_amdgcn_sched_barrier(0);
;       __builtin_amdgcn_s_setprio(1);
; #pragma unroll
;       for (int m = 0; m < MF; ++m) {
; #pragma unroll
;         for (int n = 0; n < 4; ++n) acc[m][n] = mfma16(bf[n], af[m], acc[m][n]);
;         if constexpr (MF == 8) {
;           if (m & 1) {
;             __builtin_amdgcn_sched_barrier(0);
;             if (issue) {
.LBB0_2132:
	s_mov_b32 s4, s30
	s_cmp_lt_u32 s29, 43
	s_cselect_b64 s[22:23], -1, 0
	s_lshl_b32 s4, s4, 16
	v_add3_u32 v234, s4, v178, v180
	v_add3_u32 v235, s4, v179, v180
	ds_read_b128 v[128:131], v235
	ds_read_b128 v[132:135], v235 offset:2048
	ds_read_b128 v[136:139], v235 offset:4096
	ds_read_b128 v[140:143], v235 offset:6144
	ds_read_b128 v[144:147], v234
	ds_read_b128 v[148:151], v234 offset:2048
	ds_read_b128 v[152:155], v234 offset:4096
	ds_read_b128 v[156:159], v234 offset:6144
	ds_read_b128 v[160:163], v234 offset:8192
	ds_read_b128 v[164:167], v234 offset:10240
	ds_read_b128 v[194:197], v234 offset:12288
	ds_read_b128 v[198:201], v234 offset:14336
	v_add3_u32 v234, s4, v178, v181
	v_add3_u32 v235, s4, v179, v181
	s_xor_b32 s30, s30, 1
	s_lshl_b32 s5, s30, 16
	v_readfirstlane_b32 s98, v177
	s_add_u32 s98, s98, s5
	s_cmp_eq_u64 s[22:23], 0
	s_cbranch_scc1 .Lgp12_na
	s_mov_b32 m0, s98
	s_nop 0
	global_load_lds_dwordx4 v[172:173], off
	s_add_u32 m0, s98, 0x400
	v_lshl_add_u64 v[254:255], v[172:173], 0, s[14:15]
	global_load_lds_dwordx4 v[254:255], off
	s_add_u32 m0, s98, 0x800
	v_lshl_add_u64 v[254:255], v[172:173], 0, s[16:17]
	global_load_lds_dwordx4 v[254:255], off
	s_add_u32 m0, s98, 0xc00
	v_lshl_add_u64 v[254:255], v[172:173], 0, s[18:19]
	global_load_lds_dwordx4 v[254:255], off

; __global__ void __launch_bounds__(NTHREADS, 2) mega(Params p, int ph_lo, int ph_hi) {
;   __shared__ __attribute__((aligned(16))) unsigned char smem[SMEM_BYTES];
	.amdhsa_kernel _Z4mega6Paramsii
		.amdhsa_group_segment_fixed_size 131100
		.amdhsa_private_segment_fixed_size 0
		.amdhsa_kernarg_size 560
		.amdhsa_user_sgpr_count 2
		.amdhsa_user_sgpr_dispatch_ptr 0
		.amdhsa_user_sgpr_queue_ptr 0
		.amdhsa_user_sgpr_kernarg_segment_ptr 1
		.amdhsa_user_sgpr_dispatch_id 0
		.amdhsa_user_sgpr_kernarg_preload_length 0
		.amdhsa_user_sgpr_kernarg_preload_offset 0
		.amdhsa_user_sgpr_private_segment_size 0
		.amdhsa_uses_dynamic_stack 0
		.amdhsa_enable_private_segment 0
		.amdhsa_system_sgpr_workgroup_id_x 1
		.amdhsa_system_sgpr_workgroup_id_y 0
		.amdhsa_system_sgpr_workgroup_id_z 0
		.amdhsa_system_sgpr_workgroup_info 0
		.amdhsa_system_vgpr_workitem_id 2
		.amdhsa_next_free_vgpr 256
		.amdhsa_next_free_sgpr 102
		.amdhsa_accum_offset 256
		.amdhsa_reserve_vcc 1
		.amdhsa_float_round_mode_32 0
		.amdhsa_float_round_mode_16_64 0
		.amdhsa_float_denorm_mode_32 3
		.amdhsa_float_denorm_mode_16_64 3
		.amdhsa_dx10_clamp 1
		.amdhsa_ieee_mode 1
		.amdhsa_fp16_overflow 0
		.amdhsa_tg_split 0
		.amdhsa_exception_fp_ieee_invalid_op 0
		.amdhsa_exception_fp_denorm_src 0
		.amdhsa_exception_fp_ieee_div_zero 0
		.amdhsa_exception_fp_ieee_overflow 0
		.amdhsa_exception_fp_ieee_underflow 0
		.amdhsa_exception_fp_ieee_inexact 0
		.amdhsa_exception_int_div_zero 0
	.end_amdhsa_kernel

; __global__ void __launch_bounds__(NTHREADS, 2) mega(Params p, int ph_lo, int ph_hi) {
;   __shared__ __attribute__((aligned(16))) unsigned char smem[SMEM_BYTES];
amdhsa.kernels:
  - .agpr_count:     0
    .args:
      - .offset:         0
        .size:           296
        .value_kind:     by_value
      - .offset:         296
        .size:           4
        .value_kind:     by_value
      - .offset:         300
        .size:           4
        .value_kind:     by_value
      - .offset:         304
        .size:           4
        .value_kind:     hidden_block_count_x
      - .offset:         308
        .size:           4
        .value_kind:     hidden_block_count_y
      - .offset:         312
        .size:           4
        .value_kind:     hidden_block_count_z
      - .offset:         316
        .size:           2
        .value_kind:     hidden_group_size_x
      - .offset:         318
        .size:           2
        .value_kind:     hidden_group_size_y
      - .offset:         320
        .size:           2
        .value_kind:     hidden_group_size_z
      - .offset:         322
        .size:           2
        .value_kind:     hidden_remainder_x
      - .offset:         324
        .size:           2
        .value_kind:     hidden_remainder_y
      - .offset:         326
        .size:           2
        .value_kind:     hidden_remainder_z
      - .offset:         344
        .size:           8
        .value_kind:     hidden_global_offset_x
      - .offset:         352
        .size:           8
        .value_kind:     hidden_global_offset_y
      - .offset:         360
        .size:           8
        .value_kind:     hidden_global_offset_z
      - .offset:         368
        .size:           2
        .value_kind:     hidden_grid_dims
      - .offset:         392
        .size:           8
        .value_kind:     hidden_multigrid_sync_arg
    .group_segment_fixed_size: 131100
    .kernarg_segment_align: 8
    .kernarg_segment_size: 560
    .language:       OpenCL C
    .language_version:
      - 2
      - 0
    .max_flat_workgroup_size: 512
    .name:           _Z4mega6Paramsii
    .private_segment_fixed_size: 0
    .sgpr_count:     108
    .sgpr_spill_count: 71
    .symbol:         _Z4mega6Paramsii.kd
    .uniform_work_group_size: 1
    .uses_dynamic_stack: false
    .vgpr_count:     256
    .vgpr_spill_count: 0
    .wavefront_size: 64
